# P8 conv-FFN fused into the up-projection GEMM epilogue (permuted A rows, in-lane causal conv3 + silu*v), P8 only redoes block-boundary tokens
# speedup vs baseline: 1.0504x; 1.0165x over previous
; __device__ __forceinline__ int win_dest_row(int n0) {
;     if (n0 < 5120) return n0;
;     if (n0 < 5152) return CDT + (n0 - 5120);
;     if (n0 < 7200) { const int c = n0 - 5152; return CCF + 256 * (c >> 7) + (c & 127); }
;     { const int c = n0 - 7200; return CCF + 256 * (c >> 7) + 128 + (c & 127); }
; }
; __global__ void __launch_bounds__(512, 2) mk_fwd(Args args) {
;     ...
;             if (r < I_UP) { const int nblk = FF2 / 32, kb = r / nblk, nb = r % nblk; p0_transpose_item(w_up, DM, FF2, WupT, 64 * kb, 32 * nb, 32 * nb, scr, lane, norm_ffn_w); continue; } r -= I_UP;
.Lp0t_pro_notout:
	s_sub_u32 s44, s44, 4096
	s_cmpk_lt_u32 s44, 11008
	s_cbranch_scc0 .Lp0t_pro_notup
	s_mul_hi_u32 s40, s44, 12485371
	s_mul_i32 s42, s40, 344
	s_sub_u32 s41, s44, s42
	s_mul_i32 s42, s40, 2818048
	s_lshl_b32 s43, s41, 7
	s_add_u32 s42, s42, s43
	s_add_u32 s26, s16, s42
	s_addc_u32 s27, s17, 0
	s_mov_b32 s28, 44032
	s_lshl_b32 s45, s41, 5
	s_mov_b32 s43, 0
	s_cmpk_lt_u32 s45, 5504
	s_cbranch_scc1 .Lp0t_pro_upg
	s_sub_u32 s45, s45, 5504
	s_movk_i32 s43, 128
.Lp0t_pro_upg:
	s_lshr_b32 s46, s45, 7
	s_lshl_b32 s46, s46, 8
	s_and_b32 s47, s45, 127
	s_add_u32 s46, s46, s47
	s_add_u32 s46, s46, s43
	s_lshl_b32 s42, s46, 12
	s_lshl_b32 s43, s40, 7
	s_add_u32 s42, s42, s43
	s_add_u32 s42, s42, 0x3500000
	s_add_u32 s30, s22, s42
	s_addc_u32 s31, s23, 0
	s_movk_i32 s32, 4096
	s_lshl_b32 s42, s40, 8
	s_add_u32 s34, s20, s42
	s_addc_u32 s35, s21, 0
	s_mov_b32 s33, 1
	s_branch .Lp0t_pro_decoded

; __device__ __forceinline__ int ltid() { int t = threadIdx.x; asm volatile("" : "+v"(t)); return t; }
; template <class Epi, class Sched, bool ALIGN_EPI = false, bool SP2 = false>
; __device__ __forceinline__ void gemm_phase(PG8_LAS unsigned char* lds, const Gemm g, const Sched& S, const Epi& E) {
;     const int tid = ltid(), wid = __builtin_amdgcn_readfirstlane(tid >> 6), lane = tid & 63, wr = wid >> 2, wc = wid & 3, fr = lane & 15, fq = lane >> 4;
;     const int K = g.K;
;     unsigned voffA[2], voffB[2];
; #pragma unroll
;     for (int i = 0; i < 2; ++i) { int R, C; stage_rc(tid * 16 + i * 8192, R, C); const int Rb = Epi::PERM ? ((R & ~31) + perm32(R & 31)) : R;
;         voffA[i] = (unsigned)(R * K + C) * 2u; voffB[i] = (unsigned)(Rb * K + C) * 2u; }
;     const size_t kstep = (size_t)(BK * 2);
;     const size_t hstep = (size_t)HALF * K * 2;
;     const size_t tstep = 2 * hstep;
;     const unsigned ldsw = (unsigned)wid * 1024u;
;     const int aoff = lds_byte(wr * 64 + fr, fq * 8), boff = lds_byte(wc * 32 + fr, fq * 8);
;     ...
;     unsigned long long cur = S.nextp(0), nxt; int ui = 0;
;     if (!cur) return;
;     f32x4 acc[2][2][4][2];
; #pragma unroll
;     for (int a = 0; a < 2; ++a)
; #pragma unroll
;         for (int b = 0; b < 2; ++b)
; #pragma unroll
;             for (int m = 0; m < 4; ++m)
; #pragma unroll
;                 for (int n = 0; n < 2; ++n) acc[a][b][m][n] = (f32x4){0.f, 0.f, 0.f, 0.f};
;     bf16x8 At[4][2], B0[2][2], B1[2][2];
;     const char* cA = (const char*)g.A + (size_t)UP_PM(cur) * tstep + (size_t)UP_KT0(cur) * kstep; const char* cB = (const char*)g.Bt + (size_t)UP_PN(cur) * tstep + (size_t)UP_KT0(cur) * kstep;
;     if constexpr (SP2) {
;         PG8_STAGE(PG8_SB(0, 0), cB, voffB); PG8_STAGE(PG8_SB(0, 1), cB + hstep, voffB); PG8_STAGE(PG8_SA(0, 0), cA, voffA); PG8_STAGE(PG8_SA(0, 1), cA + hstep, voffA);
;         if (wr == 1) PG8_BAR;
;         PG8_WAIT_V(2); PG8_BAR;
;         PG8_STAGE(PG8_SB(1, 0), cB + kstep, voffB); PG8_STAGE(PG8_SA(1, 0), cA + kstep, voffA); PG8_STAGE(PG8_SB(1, 1), cB + hstep + kstep, voffB);
;         PG8_WAIT_V(6); PG8_BAR;
;     } else {
;         PG8_STAGE(PG8_SB(0, 0), cB, voffB); PG8_STAGE(PG8_SA(0, 0), cA, voffA); PG8_STAGE(PG8_SB(0, 1), cB + hstep, voffB); PG8_STAGE(PG8_SA(0, 1), cA + hstep, voffA);
;         if (wr == 1) PG8_BAR;
;         PG8_WAIT_V(4); PG8_BAR;
.LBB0_796:
	s_cmp_eq_u64 s[6:7], 0
	s_cbranch_scc1 .LBB0_822
	v_ashrrev_i32_e32 v1, 31, v8
	v_lshrrev_b32_e32 v1, 26, v1
	v_add_u32_e32 v1, v8, v1
	v_ashrrev_i32_e32 v9, 6, v1
	v_bfe_i32 v1, v8, 27, 1
	v_lshlrev_b32_e32 v0, 4, v8
	v_lshrrev_b32_e32 v1, 22, v1
	v_add_u32_e32 v1, v0, v1
	v_and_b32_e32 v1, 0xfffffc00, v1
	v_sub_u32_e32 v1, v0, v1
	v_lshrrev_b32_e32 v2, 4, v1
	v_bitop3_b32 v2, v2, v1, 32 bitop3:0x6c
	v_ashrrev_i32_e32 v1, 31, v1
	v_lshrrev_b32_e32 v1, 26, v1
	v_add_u32_e32 v1, v2, v1
	v_ashrrev_i32_e32 v10, 6, v1
	v_lshlrev_b32_e32 v3, 3, v9
	v_mul_i32_i24_e32 v4, 64, v10
	v_and_b32_e32 v3, -16, v3
	v_sub_u32_e32 v2, v2, v4
	v_mov_b32_e32 v4, 1
	v_add_u32_e32 v1, v10, v3
	v_lshlrev_b32_e32 v3, 5, v9
	v_ashrrev_i16_sdwa v2, v4, sext(v2) dst_sel:DWORD dst_unused:UNUSED_PAD src0_sel:DWORD src1_sel:BYTE_0
	v_and_b32_e32 v3, 32, v3
	v_bfe_i32 v11, v2, 0, 16
	v_and_b32_e32 v6, 3, v10
	s_mov_b32 s8, 0xfffe0
	v_add_lshl_u32 v3, v3, v11, 1
	v_add_u32_e32 v0, 0x2000, v0
	v_lshlrev_b32_e32 v2, 1, v1
	v_lshrrev_b32_e32 v5, 2, v1
	v_and_or_b32 v6, v1, s8, v6
	v_and_b32_e32 v230, 15, v1
	v_bfe_u32 v231, v1, 4, 2
	v_lshl_add_u32 v230, v230, 2, v231
	v_and_b32_e32 v231, 0xffffffc0, v1
	v_or_b32_e32 v230, v230, v231
	v_lshl_add_u32 v128, v230, 12, v3
	v_ashrrev_i32_e32 v1, 31, v0
	v_lshrrev_b32_e32 v1, 22, v1
	v_add_u32_e32 v1, v0, v1
	v_ashrrev_i32_e32 v12, 10, v1
	v_mul_i32_i24_e32 v1, 0x400, v12
	v_sub_u32_e32 v0, v0, v1
	v_and_b32_e32 v2, 24, v2
	v_and_b32_e32 v5, 4, v5
	v_lshrrev_b32_e32 v1, 4, v0
	v_or3_b32 v2, v6, v5, v2
	v_bitop3_b32 v0, v1, v0, 32 bitop3:0x6c
	v_lshl_add_u32 v130, v2, 12, v3
	v_ashrrev_i32_e32 v2, 31, v0
	v_lshrrev_b32_e32 v2, 26, v2
	s_waitcnt lgkmcnt(0)
	s_add_u32 s3, s4, 0x7580000
	v_add_u32_e32 v2, v0, v2
	s_addc_u32 s33, s5, 0
	v_lshlrev_b32_e32 v1, 3, v12
	v_ashrrev_i32_e32 v13, 6, v2
	v_and_b32_e32 v2, 0xc0, v2
	s_add_u32 s38, s4, 0x3500000
	v_and_b32_e32 v1, -16, v1
	v_sub_u32_e32 v0, v0, v2
	s_addc_u32 s39, s5, 0
	v_add_u32_e32 v1, v13, v1
	v_ashrrev_i16_sdwa v0, v4, sext(v0) dst_sel:DWORD dst_unused:UNUSED_PAD src0_sel:DWORD src1_sel:BYTE_0
	v_and_b32_e32 v4, 3, v13
	s_bfe_u32 s9, s6, 0x80010
	v_and_or_b32 v4, v1, s8, v4
	s_ashr_i32 s13, s12, 6
	s_lshl_b32 s8, s6, 20
	s_lshl_b32 s14, s9, 7
	s_lshl_b32 s9, s6, 12
	s_ashr_i32 s7, s12, 8
	s_lshl_b32 s40, s13, 10
	s_and_b32 s8, s8, 0xff00000
	s_and_b32 s9, s9, 0xff00000
	s_add_u32 s9, s38, s9
	s_addc_u32 s11, s39, 0
	s_add_u32 s10, s9, s14
	s_addc_u32 s11, s11, 0
	s_add_i32 s41, s40, 0
	s_add_i32 m0, s41, 0x10000
	v_lshlrev_b32_e32 v3, 5, v12
	v_bfe_i32 v14, v0, 0, 16
	v_lshlrev_b32_e32 v0, 1, v1
	v_lshrrev_b32_e32 v2, 2, v1
	global_load_lds_dwordx4 v130, s[10:11]
	s_add_i32 m0, s41, 0x12000
	v_and_b32_e32 v3, 32, v3
	v_and_b32_e32 v0, 24, v0
	v_and_b32_e32 v2, 4, v2
	s_add_u32 s15, s3, s8
	v_or3_b32 v0, v4, v2, v0
	v_add_lshl_u32 v2, v3, v14, 1
	s_addc_u32 s16, s33, 0
	v_lshl_add_u32 v134, v0, 12, v2
	s_add_u32 s8, s10, 0x80000
	global_load_lds_dwordx4 v134, s[10:11]
	s_addc_u32 s9, s11, 0
	s_add_i32 m0, s41, 0x14000
	v_and_b32_e32 v230, 15, v1
	v_bfe_u32 v231, v1, 4, 2
	v_lshl_add_u32 v230, v230, 2, v231
	v_and_b32_e32 v231, 0xffffffc0, v1
	v_or_b32_e32 v230, v230, v231
	v_lshl_add_u32 v132, v230, 12, v2
	global_load_lds_dwordx4 v130, s[8:9]
	s_add_i32 m0, s41, 0x16000
	v_mov_b32_e32 v137, 0
	global_load_lds_dwordx4 v134, s[8:9]
	s_add_u32 s8, s15, s14
	s_addc_u32 s9, s16, 0
	s_add_i32 s42, s41, 0x2000
	s_mov_b32 m0, s41
	s_add_u32 s14, s8, 0x80000
	global_load_lds_dwordx4 v128, s[8:9]
	s_mov_b32 m0, s42
	s_addc_u32 s15, s9, 0
	s_add_i32 s43, s41, 0x4000
	global_load_lds_dwordx4 v132, s[8:9]
	s_mov_b32 m0, s43
	s_add_i32 s44, s41, 0x6000
	global_load_lds_dwordx4 v128, s[14:15]
	s_mov_b32 m0, s44
	v_mov_b32_e32 v131, v137
	global_load_lds_dwordx4 v132, s[14:15]
	v_mov_b32_e32 v135, v137
	v_mov_b32_e32 v129, v137
	v_mov_b32_e32 v133, v137
	s_cmp_eq_u32 s7, 1
	s_mov_b32 s45, 0
	v_lshl_add_u64 v[6:7], s[10:11], 0, v[130:131]
	v_lshl_add_u64 v[4:5], s[10:11], 0, v[134:135]
	v_lshl_add_u64 v[0:1], s[8:9], 0, v[128:129]
	s_cselect_b64 s[20:21], -1, 0
	s_cmp_lg_u32 s7, 1
	v_lshl_add_u64 v[2:3], s[8:9], 0, v[132:133]
	s_cbranch_scc1 .LBB0_799
	s_barrier
.LBB0_799:
	s_add_u32 s22, s4, 0x9890000
	s_addc_u32 s23, s5, 0
	s_add_u32 s24, s4, 0x1f0e0000
	s_addc_u32 s25, s5, 0
	s_lshl_b32 s4, s13, 5
	s_mov_b64 s[26:27], 0x80
	s_and_b32 s13, s4, 0x60
	s_add_i32 m0, s41, 0x18000
	v_lshl_add_u64 v[6:7], v[6:7], 0, s[26:27]
	s_lshl_b32 s14, s7, 13
	s_lshl_b32 s15, s13, 7
	s_waitcnt vmcnt(2)
	s_barrier
	global_load_lds_dwordx4 v[6:7], off
	v_lshl_add_u64 v[4:5], v[4:5], 0, s[26:27]
	s_add_i32 m0, s41, 0x1a000
	s_add_i32 s46, s41, 0x8000
	s_add_i32 s47, s41, 0xa000
	global_load_lds_dwordx4 v[4:5], off
	v_lshl_add_u64 v[0:1], v[0:1], 0, s[26:27]
	s_mov_b32 m0, s46
	s_add_u32 s4, s10, 0x80080
	global_load_lds_dwordx4 v[0:1], off
	v_lshl_add_u64 v[0:1], v[2:3], 0, s[26:27]
	s_mov_b32 m0, s47
	s_addc_u32 s5, s11, 0
	global_load_lds_dwordx4 v[0:1], off
	s_add_i32 m0, s41, 0x1c000
	v_lshl_add_u64 v[0:1], s[4:5], 0, v[130:131]
	global_load_lds_dwordx4 v[0:1], off
	v_lshl_add_u64 v[0:1], s[4:5], 0, v[134:135]
	s_add_i32 m0, s41, 0x1e000
	s_cmpk_lt_u32 s12, 0x100
	global_load_lds_dwordx4 v[0:1], off
	v_lshrrev_b32_e32 v1, 1, v8
	v_and_b32_e32 v1, 24, v1
	v_and_b32_e32 v0, 15, v8
	v_lshlrev_b32_e32 v2, 1, v1
	v_lshl_or_b32 v149, s7, 6, v0
	v_lshl_or_b32 v0, v0, 6, v2
	v_lshlrev_b32_e32 v2, 2, v8
	v_and_b32_e32 v2, 32, v2
	v_bitop3_b32 v3, v0, s14, v2 bitop3:0xde
	v_bitop3_b32 v151, v0, s15, v2 bitop3:0xde
	v_lshlrev_b32_e32 v0, 15, v9
	v_and_b32_e32 v0, 0xffff0000, v0
	v_or_b32_e32 v153, s13, v1
	v_lshl_add_u32 v0, v10, 12, v0
	v_and_b32_e32 v1, 1, v9
	v_lshl_or_b32 v0, v1, 6, v0
	v_lshl_add_u32 v138, v11, 1, v0
	v_lshlrev_b32_e32 v0, 15, v12
	v_and_b32_e32 v0, 0xffff0000, v0
	s_waitcnt vmcnt(6)
	v_lshl_add_u32 v0, v13, 12, v0
	v_and_b32_e32 v1, 1, v12
	s_cselect_b64 s[28:29], -1, 0
	v_lshl_or_b32 v0, v1, 6, v0
	s_add_i32 s50, 0, 0x10000
	s_add_i32 s51, 0, 0x14000
	s_ashr_i32 s48, s94, 31
	s_ashr_i32 s49, s2, 31
	v_mov_b32_e32 v139, v137
	v_lshl_add_u32 v140, v14, 1, v0
	v_mov_b32_e32 v138, v128
	v_mov_b32_e32 v140, v132
	v_mov_b32_e32 v141, v137
	v_mov_b64_e32 v[142:143], 0x5b5
	v_add_u32_e32 v154, s50, v151
	v_add_u32_e32 v155, s51, v151
	v_add_u32_e32 v156, 0, v3
	v_mov_b32_e32 v157, 0x3727c5ac
	s_mov_b32 s52, 0x800000
	s_movk_i32 s53, 0x5600
	s_barrier
	s_branch .LBB0_802

; #define LD8(dst, ptr) do { const f32x4 a_ = *(const f32x4*)(ptr), b_ = *(const f32x4*)((ptr) + 4); dst[0] = a_.x; dst[1] = a_.y; dst[2] = a_.z; dst[3] = a_.w; dst[4] = b_.x; dst[5] = b_.y; dst[6] = b_.z; dst[7] = b_.w; } while (0)
;     __device__ __forceinline__ void operator()(const f32x4 (&acc)[2][2][4][2], const Unit& u, int wr, int wc, int fr, int fq) const {
;     ...
;         const int col0 = u.pn * BM + wc * 32 + 8 * fq;
;         float rs[2][4];
; #pragma unroll
;         for (int ai = 0; ai < 2; ++ai)
; #pragma unroll
;             for (int m = 0; m < 4; ++m) rs[ai][m] = ssq ? rsqrtf(ssq[row0 + ai * HALF + m * 16] * (1.f / DM) + EPS) : 1.f;
; template <int NT, bool SAMPLE>
; __device__ __forceinline__ void ffn_item(const bf16_t* U, int row0, bool has_hist, const float* st, int cgi, const float* w, const float* bias, bf16_t* ACT, float* state_out) {
;     const int c0 = cgi * 8;
;     float wg[3][8], wv[3][8], bg[8], bvv[8], g0[8], g1[8], v0[8], v1[8];
;     ...
; #pragma unroll
;     for (int i = 0; i < 3; ++i) { LD8(wg[i], w + i * FF2 + c0); LD8(wv[i], w + i * FF2 + FF + c0); }
;     LD8(bg, bias + c0); LD8(bvv, bias + FF + c0);
.LBB0_817:
	s_and_b32 s7, s6, 0xff
	s_bfe_u32 s8, s6, 0x80008
	v_and_b32_e32 v144, 15, v212
	v_bfe_u32 v145, v212, 4, 2
	v_lshrrev_b32_e32 v146, 6, v212
	v_lshrrev_b32_e32 v147, 2, v146
	v_and_b32_e32 v146, 3, v146
	v_lshlrev_b32_e32 v148, 2, v144
	v_lshl_add_u32 v148, v147, 6, v148
	s_lshl_b32 s9, s7, 8
	v_add_u32_e32 v148, s9, v148
	v_lshlrev_b32_e32 v150, 3, v145
	v_lshl_add_u32 v150, v146, 5, v150
	v_lshlrev_b32_e32 v153, 2, v148
	global_load_dword v158, v153, s[24:25] offset:0
	global_load_dword v159, v153, s[24:25] offset:4
	global_load_dword v160, v153, s[24:25] offset:8
	global_load_dword v161, v153, s[24:25] offset:12
	global_load_dword v162, v153, s[24:25] offset:512
	global_load_dword v163, v153, s[24:25] offset:516
	global_load_dword v164, v153, s[24:25] offset:520
	global_load_dword v165, v153, s[24:25] offset:524
	v_mul_u32_u24_e32 v152, s53, v148
	v_lshl_add_u32 v152, v150, 1, v152
	s_lshl_b32 s9, s8, 8
	s_add_u32 s10, s22, s9
	s_addc_u32 s11, s23, 0
	s_add_u32 s12, s10, 0x2b00
	s_addc_u32 s13, s11, 0
	s_cmpk_ge_u32 s7, 32
	s_cbranch_scc1 .Lepi7_noweights
	s_load_dwordx4 s[16:19], s[96:97], 0xa8
	s_load_dwordx2 s[58:59], s[96:97], 0xc8
	v_lshlrev_b32_e32 v149, 2, v150
	s_lshl_b32 s9, s8, 9
	s_waitcnt lgkmcnt(0)
	s_add_u32 s16, s16, s9
	s_addc_u32 s17, s17, 0
	s_add_u32 s18, s18, s9
	s_addc_u32 s19, s19, 0
	global_load_dwordx4 v[176:179], v149, s[16:17] offset:0
	global_load_dwordx4 v[180:183], v149, s[16:17] offset:16
	s_add_u32 s16, s16, 0x5600
	s_addc_u32 s17, s17, 0
	global_load_dwordx4 v[184:187], v149, s[16:17] offset:0
	global_load_dwordx4 v[188:191], v149, s[16:17] offset:16
	s_add_u32 s16, s16, 0x5600
	s_addc_u32 s17, s17, 0
	global_load_dwordx4 v[192:195], v149, s[16:17] offset:0
	global_load_dwordx4 v[196:199], v149, s[16:17] offset:16
	s_add_u32 s16, s16, 0x5600
	s_addc_u32 s17, s17, 0
	global_load_dwordx4 v[200:203], v149, s[16:17] offset:0
	global_load_dwordx4 v[204:207], v149, s[16:17] offset:16
	s_add_u32 s16, s16, 0x5600
	s_addc_u32 s17, s17, 0
	global_load_dwordx4 v[208:211], v149, s[16:17] offset:0
	global_load_dwordx4 v[216:219], v149, s[16:17] offset:16
	s_add_u32 s16, s16, 0x5600
	s_addc_u32 s17, s17, 0
	global_load_dwordx4 v[220:223], v149, s[16:17] offset:0
	global_load_dwordx4 v[224:227], v149, s[16:17] offset:16
	global_load_dwordx4 v[228:231], v149, s[18:19] offset:0
	global_load_dwordx4 v[232:235], v149, s[18:19] offset:16
	s_add_u32 s18, s18, 0x5600
	s_addc_u32 s19, s19, 0
	global_load_dwordx4 v[236:239], v149, s[18:19] offset:0
	global_load_dwordx4 v[240:243], v149, s[18:19] offset:16
	v_readfirstlane_b32 s61, v147
	s_and_b32 s60, s7, 7
	s_cmp_eq_u32 s60, 7
	s_cselect_b32 s60, 1, 0
	s_and_b32 s60, s60, s61
	s_lshr_b32 s61, s7, 3
	s_mul_i32 s61, s61, 88064
	s_add_u32 s62, s58, s61
	s_addc_u32 s63, s59, 0
	s_add_u32 s62, s62, 0x4914000
	s_addc_u32 s63, s63, 0
	s_add_u32 s62, s62, s9
	s_addc_u32 s63, s63, 0
	s_add_u32 s64, s62, 0x5600
	s_addc_u32 s65, s63, 0
	s_add_u32 s66, s64, 0x5600
	s_addc_u32 s67, s65, 0
	s_add_u32 s68, s66, 0x5600
	s_addc_u32 s69, s67, 0
	s_movk_i32 s9, 0x2b00
	v_mul_u32_u24_e32 v136, s9, v148
	v_lshl_add_u32 v136, v150, 1, v136
	s_lshl_b32 s9, s8, 8
	s_add_u32 s14, s22, 0xd040000
	s_addc_u32 s15, s23, 0
	s_add_u32 s14, s14, s9
	s_addc_u32 s15, s15, 0
	s_waitcnt vmcnt(16)
	s_branch .Lepi7_rs

;     __device__ __forceinline__ void operator()(const f32x4 (&acc)[2][2][4][2], const Unit& u, int wr, int wc, int fr, int fq) const {
;     ...
;         float rs[2][4];
; #pragma unroll
;         for (int ai = 0; ai < 2; ++ai)
; #pragma unroll
;             for (int m = 0; m < 4; ++m) rs[ai][m] = ssq ? rsqrtf(ssq[row0 + ai * HALF + m * 16] * (1.f / DM) + EPS) : 1.f;
; #pragma unroll
;         for (int ai = 0; ai < 2; ++ai)
; #pragma unroll
;             for (int m = 0; m < 4; ++m) { bf16_t* rowp = O + (size_t)(row0 + ai * HALF + m * 16) * ldc + col0;
; #pragma unroll
;                 for (int bj = 0; bj < 2; ++bj) { const f32x4 v0 = acc[ai][bj][m][0] * rs[ai][m], v1 = acc[ai][bj][m][1] * rs[ai][m];
.Lepi7_rs:
	v_fmamk_f32 v158, v158, 0x3a000000, v157
	v_fmamk_f32 v159, v159, 0x3a000000, v157
	v_fmamk_f32 v160, v160, 0x3a000000, v157
	v_fmamk_f32 v161, v161, 0x3a000000, v157
	v_fmamk_f32 v162, v162, 0x3a000000, v157
	v_fmamk_f32 v163, v163, 0x3a000000, v157
	v_fmamk_f32 v164, v164, 0x3a000000, v157
	v_fmamk_f32 v165, v165, 0x3a000000, v157
	v_rsq_f32_e32 v158, v158
	v_rsq_f32_e32 v159, v159
	v_rsq_f32_e32 v160, v160
	v_rsq_f32_e32 v161, v161
	v_rsq_f32_e32 v162, v162
	v_rsq_f32_e32 v163, v163
	v_rsq_f32_e32 v164, v164
	v_rsq_f32_e32 v165, v165
	s_nop 0
	v_mul_f32_e32 v112, v112, v158
	v_mul_f32_e32 v113, v113, v158
	v_mul_f32_e32 v114, v114, v158
	v_mul_f32_e32 v115, v115, v158
	v_mul_f32_e32 v116, v116, v158
	v_mul_f32_e32 v117, v117, v158
	v_mul_f32_e32 v118, v118, v158
	v_mul_f32_e32 v119, v119, v158
	v_mul_f32_e32 v120, v120, v158
	v_mul_f32_e32 v121, v121, v158
	v_mul_f32_e32 v122, v122, v158
	v_mul_f32_e32 v123, v123, v158
	v_mul_f32_e32 v124, v124, v158
	v_mul_f32_e32 v125, v125, v158
	v_mul_f32_e32 v126, v126, v158
	v_mul_f32_e32 v127, v127, v158
	v_mul_f32_e32 v96, v96, v159
	v_mul_f32_e32 v97, v97, v159
	v_mul_f32_e32 v98, v98, v159
	v_mul_f32_e32 v99, v99, v159
	v_mul_f32_e32 v100, v100, v159
	v_mul_f32_e32 v101, v101, v159
	v_mul_f32_e32 v102, v102, v159
	v_mul_f32_e32 v103, v103, v159
	v_mul_f32_e32 v104, v104, v159
	v_mul_f32_e32 v105, v105, v159
	v_mul_f32_e32 v106, v106, v159
	v_mul_f32_e32 v107, v107, v159
	v_mul_f32_e32 v108, v108, v159
	v_mul_f32_e32 v109, v109, v159
	v_mul_f32_e32 v110, v110, v159
	v_mul_f32_e32 v111, v111, v159
	v_mul_f32_e32 v80, v80, v160
	v_mul_f32_e32 v81, v81, v160
	v_mul_f32_e32 v82, v82, v160
	v_mul_f32_e32 v83, v83, v160
	v_mul_f32_e32 v84, v84, v160
	v_mul_f32_e32 v85, v85, v160
	v_mul_f32_e32 v86, v86, v160
	v_mul_f32_e32 v87, v87, v160
	v_mul_f32_e32 v88, v88, v160
	v_mul_f32_e32 v89, v89, v160
	v_mul_f32_e32 v90, v90, v160
	v_mul_f32_e32 v91, v91, v160
	v_mul_f32_e32 v92, v92, v160
	v_mul_f32_e32 v93, v93, v160
	v_mul_f32_e32 v94, v94, v160
	v_mul_f32_e32 v95, v95, v160
	v_mul_f32_e32 v64, v64, v161
	v_mul_f32_e32 v65, v65, v161
	v_mul_f32_e32 v66, v66, v161
	v_mul_f32_e32 v67, v67, v161
	v_mul_f32_e32 v68, v68, v161
	v_mul_f32_e32 v69, v69, v161
	v_mul_f32_e32 v70, v70, v161
	v_mul_f32_e32 v71, v71, v161
	v_mul_f32_e32 v72, v72, v161
	v_mul_f32_e32 v73, v73, v161
	v_mul_f32_e32 v74, v74, v161
	v_mul_f32_e32 v75, v75, v161
	v_mul_f32_e32 v76, v76, v161
	v_mul_f32_e32 v77, v77, v161
	v_mul_f32_e32 v78, v78, v161
	v_mul_f32_e32 v79, v79, v161
	v_mul_f32_e32 v48, v48, v162
	v_mul_f32_e32 v49, v49, v162
	v_mul_f32_e32 v50, v50, v162
	v_mul_f32_e32 v51, v51, v162
	v_mul_f32_e32 v52, v52, v162
	v_mul_f32_e32 v53, v53, v162
	v_mul_f32_e32 v54, v54, v162
	v_mul_f32_e32 v55, v55, v162
	v_mul_f32_e32 v56, v56, v162
	v_mul_f32_e32 v57, v57, v162
	v_mul_f32_e32 v58, v58, v162
	v_mul_f32_e32 v59, v59, v162
	v_mul_f32_e32 v60, v60, v162
	v_mul_f32_e32 v61, v61, v162
	v_mul_f32_e32 v62, v62, v162
	v_mul_f32_e32 v63, v63, v162
	v_mul_f32_e32 v32, v32, v163
	v_mul_f32_e32 v33, v33, v163
	v_mul_f32_e32 v34, v34, v163
	v_mul_f32_e32 v35, v35, v163
	v_mul_f32_e32 v36, v36, v163
	v_mul_f32_e32 v37, v37, v163
	v_mul_f32_e32 v38, v38, v163
	v_mul_f32_e32 v39, v39, v163
	v_mul_f32_e32 v40, v40, v163
	v_mul_f32_e32 v41, v41, v163
	v_mul_f32_e32 v42, v42, v163
	v_mul_f32_e32 v43, v43, v163
	v_mul_f32_e32 v44, v44, v163
	v_mul_f32_e32 v45, v45, v163
	v_mul_f32_e32 v46, v46, v163
	v_mul_f32_e32 v47, v47, v163
	v_mul_f32_e32 v16, v16, v164
	v_mul_f32_e32 v17, v17, v164
	v_mul_f32_e32 v18, v18, v164
	v_mul_f32_e32 v19, v19, v164
	v_mul_f32_e32 v20, v20, v164
	v_mul_f32_e32 v21, v21, v164
	v_mul_f32_e32 v22, v22, v164
	v_mul_f32_e32 v23, v23, v164
	v_mul_f32_e32 v24, v24, v164
	v_mul_f32_e32 v25, v25, v164
	v_mul_f32_e32 v26, v26, v164
	v_mul_f32_e32 v27, v27, v164
	v_mul_f32_e32 v28, v28, v164
	v_mul_f32_e32 v29, v29, v164
	v_mul_f32_e32 v30, v30, v164
	v_mul_f32_e32 v31, v31, v164
	v_mul_f32_e32 v0, v0, v165
	v_mul_f32_e32 v1, v1, v165
	v_mul_f32_e32 v2, v2, v165
	v_mul_f32_e32 v3, v3, v165
	v_mul_f32_e32 v4, v4, v165
	v_mul_f32_e32 v5, v5, v165
	v_mul_f32_e32 v6, v6, v165
	v_mul_f32_e32 v7, v7, v165
	v_mul_f32_e32 v8, v8, v165
	v_mul_f32_e32 v9, v9, v165
	v_mul_f32_e32 v10, v10, v165
	v_mul_f32_e32 v11, v11, v165
	v_mul_f32_e32 v12, v12, v165
	v_mul_f32_e32 v13, v13, v165
	v_mul_f32_e32 v14, v14, v165
	v_mul_f32_e32 v15, v15, v165
	s_cmpk_ge_u32 s7, 32
	s_cbranch_scc1 .Lepi7_sample
; __device__ __forceinline__ unsigned cvt_pk_bf16(float lo, float hi) { unsigned r; asm volatile("v_cvt_pk_bf16_f32 %0, %1, %2" : "=v"(r) : "v"(lo), "v"(hi)); return r; }
; #define ST8(ptr, src) do { *(f32x4*)(ptr) = (f32x4){src[0], src[1], src[2], src[3]}; *(f32x4*)((ptr) + 4) = (f32x4){src[4], src[5], src[6], src[7]}; } while (0)
;     __device__ __forceinline__ void operator()(const f32x4 (&acc)[2][2][4][2], const Unit& u, int wr, int wc, int fr, int fq) const {
;     ...
;             for (int m = 0; m < 4; ++m) { bf16_t* rowp = O + (size_t)(row0 + ai * HALF + m * 16) * ldc + col0;
; #pragma unroll
;                 for (int bj = 0; bj < 2; ++bj) { const f32x4 v0 = acc[ai][bj][m][0] * rs[ai][m], v1 = acc[ai][bj][m][1] * rs[ai][m];
;                     u32x4 w; w.x = cvt_pk_bf16(v0[0], v0[1]); w.y = cvt_pk_bf16(v0[2], v0[3]); w.z = cvt_pk_bf16(v1[0], v1[1]); w.w = cvt_pk_bf16(v1[2], v1[3]);
;                     *(u32x4*)(rowp + bj * HALF) = w; } }
; template <int NT, bool SAMPLE>
; __device__ __forceinline__ void ffn_item(const bf16_t* U, int row0, bool has_hist, const float* st, int cgi, const float* w, const float* bias, bf16_t* ACT, float* state_out) {
;     ...
;     if (state_out) {
;     ...
;         ST8(state_out + 0 * FF2 + c0, g0); ST8(state_out + 1 * FF2 + c0, g1); ST8(state_out + 0 * FF2 + FF + c0, v0); ST8(state_out + 1 * FF2 + FF + c0, v1);
;     ...
;     }
	v_cvt_pk_bf16_f32 v168, v124, v125
	v_cvt_pk_bf16_f32 v169, v126, v127
	v_cvt_pk_bf16_f32 v170, v120, v121
	v_cvt_pk_bf16_f32 v171, v122, v123
	v_cvt_pk_bf16_f32 v172, v116, v117
	v_cvt_pk_bf16_f32 v173, v118, v119
	v_cvt_pk_bf16_f32 v174, v112, v113
	v_cvt_pk_bf16_f32 v175, v114, v115
	s_mov_b32 exec_lo, 0x00030003
	s_mov_b32 exec_hi, 0x00030003
	global_store_dwordx4 v152, v[168:171], s[10:11]
	global_store_dwordx4 v152, v[172:175], s[12:13]
	s_mov_b64 exec, -1
	s_add_u32 s10, s10, 0x5600
	s_addc_u32 s11, s11, 0
	s_add_u32 s12, s12, 0x5600
	s_addc_u32 s13, s13, 0
	v_cvt_pk_bf16_f32 v168, v108, v109
	v_cvt_pk_bf16_f32 v169, v110, v111
	v_cvt_pk_bf16_f32 v170, v104, v105
	v_cvt_pk_bf16_f32 v171, v106, v107
	v_cvt_pk_bf16_f32 v172, v100, v101
	v_cvt_pk_bf16_f32 v173, v102, v103
	v_cvt_pk_bf16_f32 v174, v96, v97
	v_cvt_pk_bf16_f32 v175, v98, v99
	s_mov_b32 exec_lo, 0x00030003
	s_mov_b32 exec_hi, 0x00030003
	global_store_dwordx4 v152, v[168:171], s[10:11]
	global_store_dwordx4 v152, v[172:175], s[12:13]
	s_mov_b64 exec, -1
	s_add_u32 s10, s10, 0x5600
	s_addc_u32 s11, s11, 0
	s_add_u32 s12, s12, 0x5600
	s_addc_u32 s13, s13, 0
	v_cvt_pk_bf16_f32 v168, v92, v93
	v_cvt_pk_bf16_f32 v169, v94, v95
	v_cvt_pk_bf16_f32 v170, v88, v89
	v_cvt_pk_bf16_f32 v171, v90, v91
	v_cvt_pk_bf16_f32 v172, v84, v85
	v_cvt_pk_bf16_f32 v173, v86, v87
	v_cvt_pk_bf16_f32 v174, v80, v81
	v_cvt_pk_bf16_f32 v175, v82, v83
	s_mov_b32 exec_lo, 0x80038003
	s_mov_b32 exec_hi, 0x80038003
	global_store_dwordx4 v152, v[168:171], s[10:11]
	global_store_dwordx4 v152, v[172:175], s[12:13]
	s_mov_b64 exec, -1
	s_add_u32 s10, s10, 0x5600
	s_addc_u32 s11, s11, 0
	s_add_u32 s12, s12, 0x5600
	s_addc_u32 s13, s13, 0
	v_cvt_pk_bf16_f32 v168, v76, v77
	v_cvt_pk_bf16_f32 v169, v78, v79
	v_cvt_pk_bf16_f32 v170, v72, v73
	v_cvt_pk_bf16_f32 v171, v74, v75
	v_cvt_pk_bf16_f32 v172, v68, v69
	v_cvt_pk_bf16_f32 v173, v70, v71
	v_cvt_pk_bf16_f32 v174, v64, v65
	v_cvt_pk_bf16_f32 v175, v66, v67
	s_mov_b32 exec_lo, 0x80038003
	s_mov_b32 exec_hi, 0x80038003
	global_store_dwordx4 v152, v[168:171], s[10:11]
	global_store_dwordx4 v152, v[172:175], s[12:13]
	s_mov_b64 exec, -1
	s_add_u32 s10, s10, 0x29fe00
	s_addc_u32 s11, s11, 0
	s_add_u32 s12, s12, 0x29fe00
	s_addc_u32 s13, s13, 0
	v_cvt_pk_bf16_f32 v168, v60, v61
	v_cvt_pk_bf16_f32 v169, v62, v63
	v_cvt_pk_bf16_f32 v170, v56, v57
	v_cvt_pk_bf16_f32 v171, v58, v59
	v_cvt_pk_bf16_f32 v172, v52, v53
	v_cvt_pk_bf16_f32 v173, v54, v55
	v_cvt_pk_bf16_f32 v174, v48, v49
	v_cvt_pk_bf16_f32 v175, v50, v51
	s_mov_b32 exec_lo, 0x00030003
	s_mov_b32 exec_hi, 0x00030003
	global_store_dwordx4 v152, v[168:171], s[10:11]
	global_store_dwordx4 v152, v[172:175], s[12:13]
	s_mov_b64 exec, -1
	s_add_u32 s10, s10, 0x5600
	s_addc_u32 s11, s11, 0
	s_add_u32 s12, s12, 0x5600
	s_addc_u32 s13, s13, 0
	v_cvt_pk_bf16_f32 v168, v44, v45
	v_cvt_pk_bf16_f32 v169, v46, v47
	v_cvt_pk_bf16_f32 v170, v40, v41
	v_cvt_pk_bf16_f32 v171, v42, v43
	v_cvt_pk_bf16_f32 v172, v36, v37
	v_cvt_pk_bf16_f32 v173, v38, v39
	v_cvt_pk_bf16_f32 v174, v32, v33
	v_cvt_pk_bf16_f32 v175, v34, v35
	s_mov_b32 exec_lo, 0x00030003
	s_mov_b32 exec_hi, 0x00030003
	global_store_dwordx4 v152, v[168:171], s[10:11]
	global_store_dwordx4 v152, v[172:175], s[12:13]
	s_mov_b64 exec, -1
	s_add_u32 s10, s10, 0x5600
	s_addc_u32 s11, s11, 0
	s_add_u32 s12, s12, 0x5600
	s_addc_u32 s13, s13, 0
	v_cvt_pk_bf16_f32 v168, v28, v29
	v_cvt_pk_bf16_f32 v169, v30, v31
	v_cvt_pk_bf16_f32 v170, v24, v25
	v_cvt_pk_bf16_f32 v171, v26, v27
	v_cvt_pk_bf16_f32 v172, v20, v21
	v_cvt_pk_bf16_f32 v173, v22, v23
	v_cvt_pk_bf16_f32 v174, v16, v17
	v_cvt_pk_bf16_f32 v175, v18, v19
	s_mov_b32 exec_lo, 0x80038003
	s_mov_b32 exec_hi, 0x80038003
	global_store_dwordx4 v152, v[168:171], s[10:11]
	global_store_dwordx4 v152, v[172:175], s[12:13]
	s_mov_b64 exec, -1
	s_cmp_eq_u32 s60, 0
	s_cbranch_scc1 .Lepi7_nostate2
	v_lshlrev_b32_e32 v244, 16, v168
	v_and_b32_e32 v245, 0xffff0000, v168
	v_lshlrev_b32_e32 v246, 16, v169
	v_and_b32_e32 v247, 0xffff0000, v169
	v_lshlrev_b32_e32 v248, 16, v170
	v_and_b32_e32 v249, 0xffff0000, v170
	v_lshlrev_b32_e32 v250, 16, v171
	v_and_b32_e32 v251, 0xffff0000, v171
	v_lshlrev_b32_e32 v254, 16, v172
	v_and_b32_e32 v255, 0xffff0000, v172
	v_lshlrev_b32_e32 v137, 16, v173
	v_and_b32_e32 v166, 0xffff0000, v173
	v_lshlrev_b32_e32 v167, 16, v174
	v_and_b32_e32 v213, 0xffff0000, v174
	v_lshlrev_b32_e32 v214, 16, v175
	v_and_b32_e32 v215, 0xffff0000, v175
	s_mov_b32 exec_lo, 0x80008000
	s_mov_b32 exec_hi, 0x80008000
	v_mov_b32_e32 v168, v244
	v_mov_b32_e32 v169, v245
	v_mov_b32_e32 v170, v246
	v_mov_b32_e32 v171, v247
	global_store_dwordx4 v149, v[168:171], s[62:63] offset:0
	s_nop 1
	v_mov_b32_e32 v172, v248
	v_mov_b32_e32 v173, v249
	v_mov_b32_e32 v174, v250
	v_mov_b32_e32 v175, v251
	global_store_dwordx4 v149, v[172:175], s[62:63] offset:16
	s_nop 1
	v_mov_b32_e32 v168, v254
	v_mov_b32_e32 v169, v255
	v_mov_b32_e32 v170, v137
	v_mov_b32_e32 v171, v166
	global_store_dwordx4 v149, v[168:171], s[64:65] offset:0
	s_nop 1
	v_mov_b32_e32 v172, v167
	v_mov_b32_e32 v173, v213
	v_mov_b32_e32 v174, v214
	v_mov_b32_e32 v175, v215
	global_store_dwordx4 v149, v[172:175], s[64:65] offset:16
	s_nop 1
	s_mov_b64 exec, -1
; __device__ __forceinline__ float siluf_(float x) { return x * __builtin_amdgcn_rcpf(1.f + __expf(-x)); }
; #define ST8(ptr, src) do { *(f32x4*)(ptr) = (f32x4){src[0], src[1], src[2], src[3]}; *(f32x4*)((ptr) + 4) = (f32x4){src[4], src[5], src[6], src[7]}; } while (0)
; template <int NT, bool SAMPLE>
; __device__ __forceinline__ void ffn_item(const bf16_t* U, int row0, bool has_hist, const float* st, int cgi, const float* w, const float* bias, bf16_t* ACT, float* state_out) {
;     ...
; #pragma unroll
;     for (int t = 0; t < NT; ++t) {
;         float cg_[8], cv_[8], o[8];
;         unpack8(rg[t], cg_); unpack8(rv[t], cv_);
; #pragma unroll
;         for (int e = 0; e < 8; ++e) {
;             const float gg = g0[e] * wg[0][e] + g1[e] * wg[1][e] + cg_[e] * wg[2][e] + bg[e];
;             const float vv = v0[e] * wv[0][e] + v1[e] * wv[1][e] + cv_[e] * wv[2][e] + bvv[e];
;             o[e] = siluf_(gg) * vv; g0[e] = g1[e]; g1[e] = cg_[e]; v0[e] = v1[e]; v1[e] = cv_[e]; }
;         *(u32x4*)(ACT + (size_t)(row0 + t) * FF + c0) = pack8(o);
;     }
;     if (state_out) {
;     ...
;         ST8(state_out + 0 * FF2 + c0, g0); ST8(state_out + 1 * FF2 + c0, g1); ST8(state_out + 0 * FF2 + FF + c0, v0); ST8(state_out + 1 * FF2 + FF + c0, v1);
;     ...
;     }
.Lepi7_nostate2:
	s_add_u32 s10, s10, 0x5600
	s_addc_u32 s11, s11, 0
	s_add_u32 s12, s12, 0x5600
	s_addc_u32 s13, s13, 0
	v_cvt_pk_bf16_f32 v168, v12, v13
	v_cvt_pk_bf16_f32 v169, v14, v15
	v_cvt_pk_bf16_f32 v170, v8, v9
	v_cvt_pk_bf16_f32 v171, v10, v11
	v_cvt_pk_bf16_f32 v172, v4, v5
	v_cvt_pk_bf16_f32 v173, v6, v7
	v_cvt_pk_bf16_f32 v174, v0, v1
	v_cvt_pk_bf16_f32 v175, v2, v3
	s_mov_b32 exec_lo, 0x80038003
	s_mov_b32 exec_hi, 0x80038003
	global_store_dwordx4 v152, v[168:171], s[10:11]
	global_store_dwordx4 v152, v[172:175], s[12:13]
	s_mov_b64 exec, -1
	s_cmp_eq_u32 s60, 0
	s_cbranch_scc1 .Lepi7_nostate3
	v_lshlrev_b32_e32 v244, 16, v168
	v_and_b32_e32 v245, 0xffff0000, v168
	v_lshlrev_b32_e32 v246, 16, v169
	v_and_b32_e32 v247, 0xffff0000, v169
	v_lshlrev_b32_e32 v248, 16, v170
	v_and_b32_e32 v249, 0xffff0000, v170
	v_lshlrev_b32_e32 v250, 16, v171
	v_and_b32_e32 v251, 0xffff0000, v171
	v_lshlrev_b32_e32 v254, 16, v172
	v_and_b32_e32 v255, 0xffff0000, v172
	v_lshlrev_b32_e32 v137, 16, v173
	v_and_b32_e32 v166, 0xffff0000, v173
	v_lshlrev_b32_e32 v167, 16, v174
	v_and_b32_e32 v213, 0xffff0000, v174
	v_lshlrev_b32_e32 v214, 16, v175
	v_and_b32_e32 v215, 0xffff0000, v175
	s_mov_b32 exec_lo, 0x80008000
	s_mov_b32 exec_hi, 0x80008000
	v_mov_b32_e32 v168, v244
	v_mov_b32_e32 v169, v245
	v_mov_b32_e32 v170, v246
	v_mov_b32_e32 v171, v247
	global_store_dwordx4 v149, v[168:171], s[66:67] offset:0
	s_nop 1
	v_mov_b32_e32 v172, v248
	v_mov_b32_e32 v173, v249
	v_mov_b32_e32 v174, v250
	v_mov_b32_e32 v175, v251
	global_store_dwordx4 v149, v[172:175], s[66:67] offset:16
	s_nop 1
	v_mov_b32_e32 v168, v254
	v_mov_b32_e32 v169, v255
	v_mov_b32_e32 v170, v137
	v_mov_b32_e32 v171, v166
	global_store_dwordx4 v149, v[168:171], s[68:69] offset:0
	s_nop 1
	v_mov_b32_e32 v172, v167
	v_mov_b32_e32 v173, v213
	v_mov_b32_e32 v174, v214
	v_mov_b32_e32 v175, v215
	global_store_dwordx4 v149, v[172:175], s[68:69] offset:16
	s_nop 1
	s_mov_b64 exec, -1
.Lepi7_nostate3:
	s_waitcnt vmcnt(0)
	v_mov_b32_dpp v244, v92 row_shr:1 row_mask:0xf bank_mask:0xf
	v_mov_b32_dpp v245, v76 row_shr:1 row_mask:0xf bank_mask:0xf
	v_mov_b32_dpp v246, v84 row_shr:1 row_mask:0xf bank_mask:0xf
	v_mov_b32_dpp v247, v68 row_shr:1 row_mask:0xf bank_mask:0xf
	v_fma_f32 v248, v124, v208, v228
	v_fma_f32 v254, v116, v220, v236
	v_fma_f32 v249, v108, v208, v228
	v_fma_f32 v255, v100, v220, v236
	v_fma_f32 v250, v92, v208, v228
	v_fma_f32 v137, v84, v220, v236
	v_fma_f32 v251, v76, v208, v228
	v_fma_f32 v166, v68, v220, v236
	v_fmac_f32_e32 v248, v245, v192
	v_fmac_f32_e32 v254, v247, v200
	v_fmac_f32_e32 v249, v124, v192
	v_fmac_f32_e32 v255, v116, v200
	v_fmac_f32_e32 v250, v108, v192
	v_fmac_f32_e32 v137, v100, v200
	v_fmac_f32_e32 v251, v92, v192
	v_fmac_f32_e32 v166, v84, v200
	v_fmac_f32_e32 v248, v244, v176
	v_fmac_f32_e32 v254, v246, v184
	v_fmac_f32_e32 v249, v245, v176
	v_fmac_f32_e32 v255, v247, v184
	v_fmac_f32_e32 v250, v124, v176
	v_fmac_f32_e32 v137, v116, v184
	v_fmac_f32_e32 v251, v108, v176
	v_fmac_f32_e32 v166, v100, v184
	v_mul_f32_e32 v167, 0xbfb8aa3b, v248
	v_mul_f32_e32 v213, 0xbfb8aa3b, v249
	v_mul_f32_e32 v214, 0xbfb8aa3b, v250
	v_mul_f32_e32 v215, 0xbfb8aa3b, v251
	v_exp_f32_e32 v167, v167
	v_exp_f32_e32 v213, v213
	v_exp_f32_e32 v214, v214
	v_exp_f32_e32 v215, v215
	v_add_f32_e32 v167, 1.0, v167
	v_add_f32_e32 v213, 1.0, v213
	v_add_f32_e32 v214, 1.0, v214
	v_add_f32_e32 v215, 1.0, v215
	v_rcp_f32_e32 v167, v167
	v_rcp_f32_e32 v213, v213
	v_rcp_f32_e32 v214, v214
	v_rcp_f32_e32 v215, v215
	v_mul_f32_e32 v248, v248, v254
	v_mul_f32_e32 v249, v249, v255
	v_mul_f32_e32 v250, v250, v137
	v_mul_f32_e32 v251, v251, v166
	v_mul_f32_e32 v124, v248, v167
	v_mul_f32_e32 v108, v249, v213
	v_mul_f32_e32 v92, v250, v214
	v_mul_f32_e32 v76, v251, v215
	v_mov_b32_dpp v244, v93 row_shr:1 row_mask:0xf bank_mask:0xf
	v_mov_b32_dpp v245, v77 row_shr:1 row_mask:0xf bank_mask:0xf
	v_mov_b32_dpp v246, v85 row_shr:1 row_mask:0xf bank_mask:0xf
	v_mov_b32_dpp v247, v69 row_shr:1 row_mask:0xf bank_mask:0xf
	v_fma_f32 v248, v125, v209, v229
	v_fma_f32 v254, v117, v221, v237
	v_fma_f32 v249, v109, v209, v229
	v_fma_f32 v255, v101, v221, v237
	v_fma_f32 v250, v93, v209, v229
	v_fma_f32 v137, v85, v221, v237
	v_fma_f32 v251, v77, v209, v229
	v_fma_f32 v166, v69, v221, v237
	v_fmac_f32_e32 v248, v245, v193
	v_fmac_f32_e32 v254, v247, v201
	v_fmac_f32_e32 v249, v125, v193
	v_fmac_f32_e32 v255, v117, v201
	v_fmac_f32_e32 v250, v109, v193
	v_fmac_f32_e32 v137, v101, v201
	v_fmac_f32_e32 v251, v93, v193
	v_fmac_f32_e32 v166, v85, v201
	v_fmac_f32_e32 v248, v244, v177
	v_fmac_f32_e32 v254, v246, v185
	v_fmac_f32_e32 v249, v245, v177
	v_fmac_f32_e32 v255, v247, v185
	v_fmac_f32_e32 v250, v125, v177
	v_fmac_f32_e32 v137, v117, v185
	v_fmac_f32_e32 v251, v109, v177
	v_fmac_f32_e32 v166, v101, v185
	v_mul_f32_e32 v167, 0xbfb8aa3b, v248
	v_mul_f32_e32 v213, 0xbfb8aa3b, v249
	v_mul_f32_e32 v214, 0xbfb8aa3b, v250
	v_mul_f32_e32 v215, 0xbfb8aa3b, v251
	v_exp_f32_e32 v167, v167
	v_exp_f32_e32 v213, v213
	v_exp_f32_e32 v214, v214
	v_exp_f32_e32 v215, v215
	v_add_f32_e32 v167, 1.0, v167
	v_add_f32_e32 v213, 1.0, v213
	v_add_f32_e32 v214, 1.0, v214
	v_add_f32_e32 v215, 1.0, v215
	v_rcp_f32_e32 v167, v167
	v_rcp_f32_e32 v213, v213
	v_rcp_f32_e32 v214, v214
	v_rcp_f32_e32 v215, v215
	v_mul_f32_e32 v248, v248, v254
	v_mul_f32_e32 v249, v249, v255
	v_mul_f32_e32 v250, v250, v137
	v_mul_f32_e32 v251, v251, v166
	v_mul_f32_e32 v125, v248, v167
	v_mul_f32_e32 v109, v249, v213
	v_mul_f32_e32 v93, v250, v214
	v_mul_f32_e32 v77, v251, v215
	v_mov_b32_dpp v244, v94 row_shr:1 row_mask:0xf bank_mask:0xf
; __device__ __forceinline__ float siluf_(float x) { return x * __builtin_amdgcn_rcpf(1.f + __expf(-x)); }
; template <int NT, bool SAMPLE>
; __device__ __forceinline__ void ffn_item(const bf16_t* U, int row0, bool has_hist, const float* st, int cgi, const float* w, const float* bias, bf16_t* ACT, float* state_out) {
;     ...
; #pragma unroll
;     for (int t = 0; t < NT; ++t) {
;         float cg_[8], cv_[8], o[8];
;         unpack8(rg[t], cg_); unpack8(rv[t], cv_);
; #pragma unroll
;         for (int e = 0; e < 8; ++e) {
;             const float gg = g0[e] * wg[0][e] + g1[e] * wg[1][e] + cg_[e] * wg[2][e] + bg[e];
;             const float vv = v0[e] * wv[0][e] + v1[e] * wv[1][e] + cv_[e] * wv[2][e] + bvv[e];
;             o[e] = siluf_(gg) * vv; g0[e] = g1[e]; g1[e] = cg_[e]; v0[e] = v1[e]; v1[e] = cv_[e]; }
;         *(u32x4*)(ACT + (size_t)(row0 + t) * FF + c0) = pack8(o);
	v_mov_b32_dpp v245, v78 row_shr:1 row_mask:0xf bank_mask:0xf
	v_mov_b32_dpp v246, v86 row_shr:1 row_mask:0xf bank_mask:0xf
	v_mov_b32_dpp v247, v70 row_shr:1 row_mask:0xf bank_mask:0xf
	v_fma_f32 v248, v126, v210, v230
	v_fma_f32 v254, v118, v222, v238
	v_fma_f32 v249, v110, v210, v230
	v_fma_f32 v255, v102, v222, v238
	v_fma_f32 v250, v94, v210, v230
	v_fma_f32 v137, v86, v222, v238
	v_fma_f32 v251, v78, v210, v230
	v_fma_f32 v166, v70, v222, v238
	v_fmac_f32_e32 v248, v245, v194
	v_fmac_f32_e32 v254, v247, v202
	v_fmac_f32_e32 v249, v126, v194
	v_fmac_f32_e32 v255, v118, v202
	v_fmac_f32_e32 v250, v110, v194
	v_fmac_f32_e32 v137, v102, v202
	v_fmac_f32_e32 v251, v94, v194
	v_fmac_f32_e32 v166, v86, v202
	v_fmac_f32_e32 v248, v244, v178
	v_fmac_f32_e32 v254, v246, v186
	v_fmac_f32_e32 v249, v245, v178
	v_fmac_f32_e32 v255, v247, v186
	v_fmac_f32_e32 v250, v126, v178
	v_fmac_f32_e32 v137, v118, v186
	v_fmac_f32_e32 v251, v110, v178
	v_fmac_f32_e32 v166, v102, v186
	v_mul_f32_e32 v167, 0xbfb8aa3b, v248
	v_mul_f32_e32 v213, 0xbfb8aa3b, v249
	v_mul_f32_e32 v214, 0xbfb8aa3b, v250
	v_mul_f32_e32 v215, 0xbfb8aa3b, v251
	v_exp_f32_e32 v167, v167
	v_exp_f32_e32 v213, v213
	v_exp_f32_e32 v214, v214
	v_exp_f32_e32 v215, v215
	v_add_f32_e32 v167, 1.0, v167
	v_add_f32_e32 v213, 1.0, v213
	v_add_f32_e32 v214, 1.0, v214
	v_add_f32_e32 v215, 1.0, v215
	v_rcp_f32_e32 v167, v167
	v_rcp_f32_e32 v213, v213
	v_rcp_f32_e32 v214, v214
	v_rcp_f32_e32 v215, v215
	v_mul_f32_e32 v248, v248, v254
	v_mul_f32_e32 v249, v249, v255
	v_mul_f32_e32 v250, v250, v137
	v_mul_f32_e32 v251, v251, v166
	v_mul_f32_e32 v126, v248, v167
	v_mul_f32_e32 v110, v249, v213
	v_mul_f32_e32 v94, v250, v214
	v_mul_f32_e32 v78, v251, v215
	v_mov_b32_dpp v244, v95 row_shr:1 row_mask:0xf bank_mask:0xf
	v_mov_b32_dpp v245, v79 row_shr:1 row_mask:0xf bank_mask:0xf
	v_mov_b32_dpp v246, v87 row_shr:1 row_mask:0xf bank_mask:0xf
	v_mov_b32_dpp v247, v71 row_shr:1 row_mask:0xf bank_mask:0xf
	v_fma_f32 v248, v127, v211, v231
	v_fma_f32 v254, v119, v223, v239
	v_fma_f32 v249, v111, v211, v231
	v_fma_f32 v255, v103, v223, v239
	v_fma_f32 v250, v95, v211, v231
	v_fma_f32 v137, v87, v223, v239
	v_fma_f32 v251, v79, v211, v231
	v_fma_f32 v166, v71, v223, v239
	v_fmac_f32_e32 v248, v245, v195
	v_fmac_f32_e32 v254, v247, v203
	v_fmac_f32_e32 v249, v127, v195
	v_fmac_f32_e32 v255, v119, v203
	v_fmac_f32_e32 v250, v111, v195
	v_fmac_f32_e32 v137, v103, v203
	v_fmac_f32_e32 v251, v95, v195
	v_fmac_f32_e32 v166, v87, v203
	v_fmac_f32_e32 v248, v244, v179
	v_fmac_f32_e32 v254, v246, v187
	v_fmac_f32_e32 v249, v245, v179
	v_fmac_f32_e32 v255, v247, v187
	v_fmac_f32_e32 v250, v127, v179
	v_fmac_f32_e32 v137, v119, v187
	v_fmac_f32_e32 v251, v111, v179
	v_fmac_f32_e32 v166, v103, v187
	v_mul_f32_e32 v167, 0xbfb8aa3b, v248
	v_mul_f32_e32 v213, 0xbfb8aa3b, v249
	v_mul_f32_e32 v214, 0xbfb8aa3b, v250
	v_mul_f32_e32 v215, 0xbfb8aa3b, v251
	v_exp_f32_e32 v167, v167
	v_exp_f32_e32 v213, v213
	v_exp_f32_e32 v214, v214
	v_exp_f32_e32 v215, v215
	v_add_f32_e32 v167, 1.0, v167
	v_add_f32_e32 v213, 1.0, v213
	v_add_f32_e32 v214, 1.0, v214
	v_add_f32_e32 v215, 1.0, v215
	v_rcp_f32_e32 v167, v167
	v_rcp_f32_e32 v213, v213
	v_rcp_f32_e32 v214, v214
	v_rcp_f32_e32 v215, v215
	v_mul_f32_e32 v248, v248, v254
	v_mul_f32_e32 v249, v249, v255
	v_mul_f32_e32 v250, v250, v137
	v_mul_f32_e32 v251, v251, v166
	v_mul_f32_e32 v127, v248, v167
	v_mul_f32_e32 v111, v249, v213
	v_mul_f32_e32 v95, v250, v214
	v_mul_f32_e32 v79, v251, v215
	v_mov_b32_dpp v244, v88 row_shr:1 row_mask:0xf bank_mask:0xf
	v_mov_b32_dpp v245, v72 row_shr:1 row_mask:0xf bank_mask:0xf
	v_mov_b32_dpp v246, v80 row_shr:1 row_mask:0xf bank_mask:0xf
	v_mov_b32_dpp v247, v64 row_shr:1 row_mask:0xf bank_mask:0xf
	v_fma_f32 v248, v120, v216, v232
	v_fma_f32 v254, v112, v224, v240
	v_fma_f32 v249, v104, v216, v232
	v_fma_f32 v255, v96, v224, v240
	v_fma_f32 v250, v88, v216, v232
	v_fma_f32 v137, v80, v224, v240
	v_fma_f32 v251, v72, v216, v232
	v_fma_f32 v166, v64, v224, v240
	v_fmac_f32_e32 v248, v245, v196
	v_fmac_f32_e32 v254, v247, v204
	v_fmac_f32_e32 v249, v120, v196
	v_fmac_f32_e32 v255, v112, v204
	v_fmac_f32_e32 v250, v104, v196
	v_fmac_f32_e32 v137, v96, v204
	v_fmac_f32_e32 v251, v88, v196
	v_fmac_f32_e32 v166, v80, v204
	v_fmac_f32_e32 v248, v244, v180
	v_fmac_f32_e32 v254, v246, v188
	v_fmac_f32_e32 v249, v245, v180
	v_fmac_f32_e32 v255, v247, v188
	v_fmac_f32_e32 v250, v120, v180
	v_fmac_f32_e32 v137, v112, v188
	v_fmac_f32_e32 v251, v104, v180
	v_fmac_f32_e32 v166, v96, v188
	v_mul_f32_e32 v167, 0xbfb8aa3b, v248
	v_mul_f32_e32 v213, 0xbfb8aa3b, v249
	v_mul_f32_e32 v214, 0xbfb8aa3b, v250
	v_mul_f32_e32 v215, 0xbfb8aa3b, v251
	v_exp_f32_e32 v167, v167
	v_exp_f32_e32 v213, v213
	v_exp_f32_e32 v214, v214
	v_exp_f32_e32 v215, v215
	v_add_f32_e32 v167, 1.0, v167
	v_add_f32_e32 v213, 1.0, v213
	v_add_f32_e32 v214, 1.0, v214
	v_add_f32_e32 v215, 1.0, v215
	v_rcp_f32_e32 v167, v167
	v_rcp_f32_e32 v213, v213
	v_rcp_f32_e32 v214, v214
	v_rcp_f32_e32 v215, v215
	v_mul_f32_e32 v248, v248, v254
	v_mul_f32_e32 v249, v249, v255
	v_mul_f32_e32 v250, v250, v137
	v_mul_f32_e32 v251, v251, v166
	v_mul_f32_e32 v120, v248, v167
	v_mul_f32_e32 v104, v249, v213
	v_mul_f32_e32 v88, v250, v214
	v_mul_f32_e32 v72, v251, v215
	v_mov_b32_dpp v244, v89 row_shr:1 row_mask:0xf bank_mask:0xf
	v_mov_b32_dpp v245, v73 row_shr:1 row_mask:0xf bank_mask:0xf
	v_mov_b32_dpp v246, v81 row_shr:1 row_mask:0xf bank_mask:0xf
	v_mov_b32_dpp v247, v65 row_shr:1 row_mask:0xf bank_mask:0xf
	v_fma_f32 v248, v121, v217, v233
	v_fma_f32 v254, v113, v225, v241
	v_fma_f32 v249, v105, v217, v233
; __device__ __forceinline__ float siluf_(float x) { return x * __builtin_amdgcn_rcpf(1.f + __expf(-x)); }
; template <int NT, bool SAMPLE>
; __device__ __forceinline__ void ffn_item(const bf16_t* U, int row0, bool has_hist, const float* st, int cgi, const float* w, const float* bias, bf16_t* ACT, float* state_out) {
;     ...
; #pragma unroll
;     for (int t = 0; t < NT; ++t) {
;         float cg_[8], cv_[8], o[8];
;         unpack8(rg[t], cg_); unpack8(rv[t], cv_);
; #pragma unroll
;         for (int e = 0; e < 8; ++e) {
;             const float gg = g0[e] * wg[0][e] + g1[e] * wg[1][e] + cg_[e] * wg[2][e] + bg[e];
;             const float vv = v0[e] * wv[0][e] + v1[e] * wv[1][e] + cv_[e] * wv[2][e] + bvv[e];
;             o[e] = siluf_(gg) * vv; g0[e] = g1[e]; g1[e] = cg_[e]; v0[e] = v1[e]; v1[e] = cv_[e]; }
;         *(u32x4*)(ACT + (size_t)(row0 + t) * FF + c0) = pack8(o);
	v_fma_f32 v255, v97, v225, v241
	v_fma_f32 v250, v89, v217, v233
	v_fma_f32 v137, v81, v225, v241
	v_fma_f32 v251, v73, v217, v233
	v_fma_f32 v166, v65, v225, v241
	v_fmac_f32_e32 v248, v245, v197
	v_fmac_f32_e32 v254, v247, v205
	v_fmac_f32_e32 v249, v121, v197
	v_fmac_f32_e32 v255, v113, v205
	v_fmac_f32_e32 v250, v105, v197
	v_fmac_f32_e32 v137, v97, v205
	v_fmac_f32_e32 v251, v89, v197
	v_fmac_f32_e32 v166, v81, v205
	v_fmac_f32_e32 v248, v244, v181
	v_fmac_f32_e32 v254, v246, v189
	v_fmac_f32_e32 v249, v245, v181
	v_fmac_f32_e32 v255, v247, v189
	v_fmac_f32_e32 v250, v121, v181
	v_fmac_f32_e32 v137, v113, v189
	v_fmac_f32_e32 v251, v105, v181
	v_fmac_f32_e32 v166, v97, v189
	v_mul_f32_e32 v167, 0xbfb8aa3b, v248
	v_mul_f32_e32 v213, 0xbfb8aa3b, v249
	v_mul_f32_e32 v214, 0xbfb8aa3b, v250
	v_mul_f32_e32 v215, 0xbfb8aa3b, v251
	v_exp_f32_e32 v167, v167
	v_exp_f32_e32 v213, v213
	v_exp_f32_e32 v214, v214
	v_exp_f32_e32 v215, v215
	v_add_f32_e32 v167, 1.0, v167
	v_add_f32_e32 v213, 1.0, v213
	v_add_f32_e32 v214, 1.0, v214
	v_add_f32_e32 v215, 1.0, v215
	v_rcp_f32_e32 v167, v167
	v_rcp_f32_e32 v213, v213
	v_rcp_f32_e32 v214, v214
	v_rcp_f32_e32 v215, v215
	v_mul_f32_e32 v248, v248, v254
	v_mul_f32_e32 v249, v249, v255
	v_mul_f32_e32 v250, v250, v137
	v_mul_f32_e32 v251, v251, v166
	v_mul_f32_e32 v121, v248, v167
	v_mul_f32_e32 v105, v249, v213
	v_mul_f32_e32 v89, v250, v214
	v_mul_f32_e32 v73, v251, v215
	v_mov_b32_dpp v244, v90 row_shr:1 row_mask:0xf bank_mask:0xf
	v_mov_b32_dpp v245, v74 row_shr:1 row_mask:0xf bank_mask:0xf
	v_mov_b32_dpp v246, v82 row_shr:1 row_mask:0xf bank_mask:0xf
	v_mov_b32_dpp v247, v66 row_shr:1 row_mask:0xf bank_mask:0xf
	v_fma_f32 v248, v122, v218, v234
	v_fma_f32 v254, v114, v226, v242
	v_fma_f32 v249, v106, v218, v234
	v_fma_f32 v255, v98, v226, v242
	v_fma_f32 v250, v90, v218, v234
	v_fma_f32 v137, v82, v226, v242
	v_fma_f32 v251, v74, v218, v234
	v_fma_f32 v166, v66, v226, v242
	v_fmac_f32_e32 v248, v245, v198
	v_fmac_f32_e32 v254, v247, v206
	v_fmac_f32_e32 v249, v122, v198
	v_fmac_f32_e32 v255, v114, v206
	v_fmac_f32_e32 v250, v106, v198
	v_fmac_f32_e32 v137, v98, v206
	v_fmac_f32_e32 v251, v90, v198
	v_fmac_f32_e32 v166, v82, v206
	v_fmac_f32_e32 v248, v244, v182
	v_fmac_f32_e32 v254, v246, v190
	v_fmac_f32_e32 v249, v245, v182
	v_fmac_f32_e32 v255, v247, v190
	v_fmac_f32_e32 v250, v122, v182
	v_fmac_f32_e32 v137, v114, v190
	v_fmac_f32_e32 v251, v106, v182
	v_fmac_f32_e32 v166, v98, v190
	v_mul_f32_e32 v167, 0xbfb8aa3b, v248
	v_mul_f32_e32 v213, 0xbfb8aa3b, v249
	v_mul_f32_e32 v214, 0xbfb8aa3b, v250
	v_mul_f32_e32 v215, 0xbfb8aa3b, v251
	v_exp_f32_e32 v167, v167
	v_exp_f32_e32 v213, v213
	v_exp_f32_e32 v214, v214
	v_exp_f32_e32 v215, v215
	v_add_f32_e32 v167, 1.0, v167
	v_add_f32_e32 v213, 1.0, v213
	v_add_f32_e32 v214, 1.0, v214
	v_add_f32_e32 v215, 1.0, v215
	v_rcp_f32_e32 v167, v167
	v_rcp_f32_e32 v213, v213
	v_rcp_f32_e32 v214, v214
	v_rcp_f32_e32 v215, v215
	v_mul_f32_e32 v248, v248, v254
	v_mul_f32_e32 v249, v249, v255
	v_mul_f32_e32 v250, v250, v137
	v_mul_f32_e32 v251, v251, v166
	v_mul_f32_e32 v122, v248, v167
	v_mul_f32_e32 v106, v249, v213
	v_mul_f32_e32 v90, v250, v214
	v_mul_f32_e32 v74, v251, v215
	v_mov_b32_dpp v244, v91 row_shr:1 row_mask:0xf bank_mask:0xf
	v_mov_b32_dpp v245, v75 row_shr:1 row_mask:0xf bank_mask:0xf
	v_mov_b32_dpp v246, v83 row_shr:1 row_mask:0xf bank_mask:0xf
	v_mov_b32_dpp v247, v67 row_shr:1 row_mask:0xf bank_mask:0xf
	v_fma_f32 v248, v123, v219, v235
	v_fma_f32 v254, v115, v227, v243
	v_fma_f32 v249, v107, v219, v235
	v_fma_f32 v255, v99, v227, v243
	v_fma_f32 v250, v91, v219, v235
	v_fma_f32 v137, v83, v227, v243
	v_fma_f32 v251, v75, v219, v235
	v_fma_f32 v166, v67, v227, v243
	v_fmac_f32_e32 v248, v245, v199
	v_fmac_f32_e32 v254, v247, v207
	v_fmac_f32_e32 v249, v123, v199
	v_fmac_f32_e32 v255, v115, v207
	v_fmac_f32_e32 v250, v107, v199
	v_fmac_f32_e32 v137, v99, v207
	v_fmac_f32_e32 v251, v91, v199
	v_fmac_f32_e32 v166, v83, v207
	v_fmac_f32_e32 v248, v244, v183
	v_fmac_f32_e32 v254, v246, v191
	v_fmac_f32_e32 v249, v245, v183
	v_fmac_f32_e32 v255, v247, v191
	v_fmac_f32_e32 v250, v123, v183
	v_fmac_f32_e32 v137, v115, v191
	v_fmac_f32_e32 v251, v107, v183
	v_fmac_f32_e32 v166, v99, v191
	v_mul_f32_e32 v167, 0xbfb8aa3b, v248
	v_mul_f32_e32 v213, 0xbfb8aa3b, v249
	v_mul_f32_e32 v214, 0xbfb8aa3b, v250
	v_mul_f32_e32 v215, 0xbfb8aa3b, v251
	v_exp_f32_e32 v167, v167
	v_exp_f32_e32 v213, v213
	v_exp_f32_e32 v214, v214
	v_exp_f32_e32 v215, v215
	v_add_f32_e32 v167, 1.0, v167
	v_add_f32_e32 v213, 1.0, v213
	v_add_f32_e32 v214, 1.0, v214
	v_add_f32_e32 v215, 1.0, v215
	v_rcp_f32_e32 v167, v167
	v_rcp_f32_e32 v213, v213
	v_rcp_f32_e32 v214, v214
	v_rcp_f32_e32 v215, v215
	v_mul_f32_e32 v248, v248, v254
	v_mul_f32_e32 v249, v249, v255
	v_mul_f32_e32 v250, v250, v137
	v_mul_f32_e32 v251, v251, v166
	v_mul_f32_e32 v123, v248, v167
	v_mul_f32_e32 v107, v249, v213
	v_mul_f32_e32 v91, v250, v214
	v_mul_f32_e32 v75, v251, v215
	v_mov_b32_dpp v244, v28 row_shr:1 row_mask:0xf bank_mask:0xf
	v_mov_b32_dpp v245, v12 row_shr:1 row_mask:0xf bank_mask:0xf
	v_mov_b32_dpp v246, v20 row_shr:1 row_mask:0xf bank_mask:0xf
	v_mov_b32_dpp v247, v4 row_shr:1 row_mask:0xf bank_mask:0xf
	v_fma_f32 v248, v60, v208, v228
	v_fma_f32 v254, v52, v220, v236
	v_fma_f32 v249, v44, v208, v228
	v_fma_f32 v255, v36, v220, v236
	v_fma_f32 v250, v28, v208, v228
	v_fma_f32 v137, v20, v220, v236
	v_fma_f32 v251, v12, v208, v228
	v_fma_f32 v166, v4, v220, v236
	v_fmac_f32_e32 v248, v245, v192
	v_fmac_f32_e32 v254, v247, v200
	v_fmac_f32_e32 v249, v60, v192
	v_fmac_f32_e32 v255, v52, v200
	v_fmac_f32_e32 v250, v44, v192
; __device__ __forceinline__ float siluf_(float x) { return x * __builtin_amdgcn_rcpf(1.f + __expf(-x)); }
; template <int NT, bool SAMPLE>
; __device__ __forceinline__ void ffn_item(const bf16_t* U, int row0, bool has_hist, const float* st, int cgi, const float* w, const float* bias, bf16_t* ACT, float* state_out) {
;     ...
; #pragma unroll
;     for (int t = 0; t < NT; ++t) {
;         float cg_[8], cv_[8], o[8];
;         unpack8(rg[t], cg_); unpack8(rv[t], cv_);
; #pragma unroll
;         for (int e = 0; e < 8; ++e) {
;             const float gg = g0[e] * wg[0][e] + g1[e] * wg[1][e] + cg_[e] * wg[2][e] + bg[e];
;             const float vv = v0[e] * wv[0][e] + v1[e] * wv[1][e] + cv_[e] * wv[2][e] + bvv[e];
;             o[e] = siluf_(gg) * vv; g0[e] = g1[e]; g1[e] = cg_[e]; v0[e] = v1[e]; v1[e] = cv_[e]; }
;         *(u32x4*)(ACT + (size_t)(row0 + t) * FF + c0) = pack8(o);
	v_fmac_f32_e32 v137, v36, v200
	v_fmac_f32_e32 v251, v28, v192
	v_fmac_f32_e32 v166, v20, v200
	v_fmac_f32_e32 v248, v244, v176
	v_fmac_f32_e32 v254, v246, v184
	v_fmac_f32_e32 v249, v245, v176
	v_fmac_f32_e32 v255, v247, v184
	v_fmac_f32_e32 v250, v60, v176
	v_fmac_f32_e32 v137, v52, v184
	v_fmac_f32_e32 v251, v44, v176
	v_fmac_f32_e32 v166, v36, v184
	v_mul_f32_e32 v167, 0xbfb8aa3b, v248
	v_mul_f32_e32 v213, 0xbfb8aa3b, v249
	v_mul_f32_e32 v214, 0xbfb8aa3b, v250
	v_mul_f32_e32 v215, 0xbfb8aa3b, v251
	v_exp_f32_e32 v167, v167
	v_exp_f32_e32 v213, v213
	v_exp_f32_e32 v214, v214
	v_exp_f32_e32 v215, v215
	v_add_f32_e32 v167, 1.0, v167
	v_add_f32_e32 v213, 1.0, v213
	v_add_f32_e32 v214, 1.0, v214
	v_add_f32_e32 v215, 1.0, v215
	v_rcp_f32_e32 v167, v167
	v_rcp_f32_e32 v213, v213
	v_rcp_f32_e32 v214, v214
	v_rcp_f32_e32 v215, v215
	v_mul_f32_e32 v248, v248, v254
	v_mul_f32_e32 v249, v249, v255
	v_mul_f32_e32 v250, v250, v137
	v_mul_f32_e32 v251, v251, v166
	v_mul_f32_e32 v60, v248, v167
	v_mul_f32_e32 v44, v249, v213
	v_mul_f32_e32 v28, v250, v214
	v_mul_f32_e32 v12, v251, v215
	v_mov_b32_dpp v244, v29 row_shr:1 row_mask:0xf bank_mask:0xf
	v_mov_b32_dpp v245, v13 row_shr:1 row_mask:0xf bank_mask:0xf
	v_mov_b32_dpp v246, v21 row_shr:1 row_mask:0xf bank_mask:0xf
	v_mov_b32_dpp v247, v5 row_shr:1 row_mask:0xf bank_mask:0xf
	v_fma_f32 v248, v61, v209, v229
	v_fma_f32 v254, v53, v221, v237
	v_fma_f32 v249, v45, v209, v229
	v_fma_f32 v255, v37, v221, v237
	v_fma_f32 v250, v29, v209, v229
	v_fma_f32 v137, v21, v221, v237
	v_fma_f32 v251, v13, v209, v229
	v_fma_f32 v166, v5, v221, v237
	v_fmac_f32_e32 v248, v245, v193
	v_fmac_f32_e32 v254, v247, v201
	v_fmac_f32_e32 v249, v61, v193
	v_fmac_f32_e32 v255, v53, v201
	v_fmac_f32_e32 v250, v45, v193
	v_fmac_f32_e32 v137, v37, v201
	v_fmac_f32_e32 v251, v29, v193
	v_fmac_f32_e32 v166, v21, v201
	v_fmac_f32_e32 v248, v244, v177
	v_fmac_f32_e32 v254, v246, v185
	v_fmac_f32_e32 v249, v245, v177
	v_fmac_f32_e32 v255, v247, v185
	v_fmac_f32_e32 v250, v61, v177
	v_fmac_f32_e32 v137, v53, v185
	v_fmac_f32_e32 v251, v45, v177
	v_fmac_f32_e32 v166, v37, v185
	v_mul_f32_e32 v167, 0xbfb8aa3b, v248
	v_mul_f32_e32 v213, 0xbfb8aa3b, v249
	v_mul_f32_e32 v214, 0xbfb8aa3b, v250
	v_mul_f32_e32 v215, 0xbfb8aa3b, v251
	v_exp_f32_e32 v167, v167
	v_exp_f32_e32 v213, v213
	v_exp_f32_e32 v214, v214
	v_exp_f32_e32 v215, v215
	v_add_f32_e32 v167, 1.0, v167
	v_add_f32_e32 v213, 1.0, v213
	v_add_f32_e32 v214, 1.0, v214
	v_add_f32_e32 v215, 1.0, v215
	v_rcp_f32_e32 v167, v167
	v_rcp_f32_e32 v213, v213
	v_rcp_f32_e32 v214, v214
	v_rcp_f32_e32 v215, v215
	v_mul_f32_e32 v248, v248, v254
	v_mul_f32_e32 v249, v249, v255
	v_mul_f32_e32 v250, v250, v137
	v_mul_f32_e32 v251, v251, v166
	v_mul_f32_e32 v61, v248, v167
	v_mul_f32_e32 v45, v249, v213
	v_mul_f32_e32 v29, v250, v214
	v_mul_f32_e32 v13, v251, v215
	v_mov_b32_dpp v244, v30 row_shr:1 row_mask:0xf bank_mask:0xf
	v_mov_b32_dpp v245, v14 row_shr:1 row_mask:0xf bank_mask:0xf
	v_mov_b32_dpp v246, v22 row_shr:1 row_mask:0xf bank_mask:0xf
	v_mov_b32_dpp v247, v6 row_shr:1 row_mask:0xf bank_mask:0xf
	v_fma_f32 v248, v62, v210, v230
	v_fma_f32 v254, v54, v222, v238
	v_fma_f32 v249, v46, v210, v230
	v_fma_f32 v255, v38, v222, v238
	v_fma_f32 v250, v30, v210, v230
	v_fma_f32 v137, v22, v222, v238
	v_fma_f32 v251, v14, v210, v230
	v_fma_f32 v166, v6, v222, v238
	v_fmac_f32_e32 v248, v245, v194
	v_fmac_f32_e32 v254, v247, v202
	v_fmac_f32_e32 v249, v62, v194
	v_fmac_f32_e32 v255, v54, v202
	v_fmac_f32_e32 v250, v46, v194
	v_fmac_f32_e32 v137, v38, v202
	v_fmac_f32_e32 v251, v30, v194
	v_fmac_f32_e32 v166, v22, v202
	v_fmac_f32_e32 v248, v244, v178
	v_fmac_f32_e32 v254, v246, v186
	v_fmac_f32_e32 v249, v245, v178
	v_fmac_f32_e32 v255, v247, v186
	v_fmac_f32_e32 v250, v62, v178
	v_fmac_f32_e32 v137, v54, v186
	v_fmac_f32_e32 v251, v46, v178
	v_fmac_f32_e32 v166, v38, v186
	v_mul_f32_e32 v167, 0xbfb8aa3b, v248
	v_mul_f32_e32 v213, 0xbfb8aa3b, v249
	v_mul_f32_e32 v214, 0xbfb8aa3b, v250
	v_mul_f32_e32 v215, 0xbfb8aa3b, v251
	v_exp_f32_e32 v167, v167
	v_exp_f32_e32 v213, v213
	v_exp_f32_e32 v214, v214
	v_exp_f32_e32 v215, v215
	v_add_f32_e32 v167, 1.0, v167
	v_add_f32_e32 v213, 1.0, v213
	v_add_f32_e32 v214, 1.0, v214
	v_add_f32_e32 v215, 1.0, v215
	v_rcp_f32_e32 v167, v167
	v_rcp_f32_e32 v213, v213
	v_rcp_f32_e32 v214, v214
	v_rcp_f32_e32 v215, v215
	v_mul_f32_e32 v248, v248, v254
	v_mul_f32_e32 v249, v249, v255
	v_mul_f32_e32 v250, v250, v137
	v_mul_f32_e32 v251, v251, v166
	v_mul_f32_e32 v62, v248, v167
	v_mul_f32_e32 v46, v249, v213
	v_mul_f32_e32 v30, v250, v214
	v_mul_f32_e32 v14, v251, v215
	v_mov_b32_dpp v244, v31 row_shr:1 row_mask:0xf bank_mask:0xf
	v_mov_b32_dpp v245, v15 row_shr:1 row_mask:0xf bank_mask:0xf
	v_mov_b32_dpp v246, v23 row_shr:1 row_mask:0xf bank_mask:0xf
	v_mov_b32_dpp v247, v7 row_shr:1 row_mask:0xf bank_mask:0xf
	v_fma_f32 v248, v63, v211, v231
	v_fma_f32 v254, v55, v223, v239
	v_fma_f32 v249, v47, v211, v231
	v_fma_f32 v255, v39, v223, v239
	v_fma_f32 v250, v31, v211, v231
	v_fma_f32 v137, v23, v223, v239
	v_fma_f32 v251, v15, v211, v231
	v_fma_f32 v166, v7, v223, v239
	v_fmac_f32_e32 v248, v245, v195
	v_fmac_f32_e32 v254, v247, v203
	v_fmac_f32_e32 v249, v63, v195
	v_fmac_f32_e32 v255, v55, v203
	v_fmac_f32_e32 v250, v47, v195
	v_fmac_f32_e32 v137, v39, v203
	v_fmac_f32_e32 v251, v31, v195
	v_fmac_f32_e32 v166, v23, v203
	v_fmac_f32_e32 v248, v244, v179
	v_fmac_f32_e32 v254, v246, v187
	v_fmac_f32_e32 v249, v245, v179
	v_fmac_f32_e32 v255, v247, v187
	v_fmac_f32_e32 v250, v63, v179
	v_fmac_f32_e32 v137, v55, v187
	v_fmac_f32_e32 v251, v47, v179
	v_fmac_f32_e32 v166, v39, v187
; __device__ __forceinline__ float siluf_(float x) { return x * __builtin_amdgcn_rcpf(1.f + __expf(-x)); }
; template <int NT, bool SAMPLE>
; __device__ __forceinline__ void ffn_item(const bf16_t* U, int row0, bool has_hist, const float* st, int cgi, const float* w, const float* bias, bf16_t* ACT, float* state_out) {
;     ...
; #pragma unroll
;     for (int t = 0; t < NT; ++t) {
;         float cg_[8], cv_[8], o[8];
;         unpack8(rg[t], cg_); unpack8(rv[t], cv_);
; #pragma unroll
;         for (int e = 0; e < 8; ++e) {
;             const float gg = g0[e] * wg[0][e] + g1[e] * wg[1][e] + cg_[e] * wg[2][e] + bg[e];
;             const float vv = v0[e] * wv[0][e] + v1[e] * wv[1][e] + cv_[e] * wv[2][e] + bvv[e];
;             o[e] = siluf_(gg) * vv; g0[e] = g1[e]; g1[e] = cg_[e]; v0[e] = v1[e]; v1[e] = cv_[e]; }
;         *(u32x4*)(ACT + (size_t)(row0 + t) * FF + c0) = pack8(o);
	v_mul_f32_e32 v167, 0xbfb8aa3b, v248
	v_mul_f32_e32 v213, 0xbfb8aa3b, v249
	v_mul_f32_e32 v214, 0xbfb8aa3b, v250
	v_mul_f32_e32 v215, 0xbfb8aa3b, v251
	v_exp_f32_e32 v167, v167
	v_exp_f32_e32 v213, v213
	v_exp_f32_e32 v214, v214
	v_exp_f32_e32 v215, v215
	v_add_f32_e32 v167, 1.0, v167
	v_add_f32_e32 v213, 1.0, v213
	v_add_f32_e32 v214, 1.0, v214
	v_add_f32_e32 v215, 1.0, v215
	v_rcp_f32_e32 v167, v167
	v_rcp_f32_e32 v213, v213
	v_rcp_f32_e32 v214, v214
	v_rcp_f32_e32 v215, v215
	v_mul_f32_e32 v248, v248, v254
	v_mul_f32_e32 v249, v249, v255
	v_mul_f32_e32 v250, v250, v137
	v_mul_f32_e32 v251, v251, v166
	v_mul_f32_e32 v63, v248, v167
	v_mul_f32_e32 v47, v249, v213
	v_mul_f32_e32 v31, v250, v214
	v_mul_f32_e32 v15, v251, v215
	v_mov_b32_dpp v244, v24 row_shr:1 row_mask:0xf bank_mask:0xf
	v_mov_b32_dpp v245, v8 row_shr:1 row_mask:0xf bank_mask:0xf
	v_mov_b32_dpp v246, v16 row_shr:1 row_mask:0xf bank_mask:0xf
	v_mov_b32_dpp v247, v0 row_shr:1 row_mask:0xf bank_mask:0xf
	v_fma_f32 v248, v56, v216, v232
	v_fma_f32 v254, v48, v224, v240
	v_fma_f32 v249, v40, v216, v232
	v_fma_f32 v255, v32, v224, v240
	v_fma_f32 v250, v24, v216, v232
	v_fma_f32 v137, v16, v224, v240
	v_fma_f32 v251, v8, v216, v232
	v_fma_f32 v166, v0, v224, v240
	v_fmac_f32_e32 v248, v245, v196
	v_fmac_f32_e32 v254, v247, v204
	v_fmac_f32_e32 v249, v56, v196
	v_fmac_f32_e32 v255, v48, v204
	v_fmac_f32_e32 v250, v40, v196
	v_fmac_f32_e32 v137, v32, v204
	v_fmac_f32_e32 v251, v24, v196
	v_fmac_f32_e32 v166, v16, v204
	v_fmac_f32_e32 v248, v244, v180
	v_fmac_f32_e32 v254, v246, v188
	v_fmac_f32_e32 v249, v245, v180
	v_fmac_f32_e32 v255, v247, v188
	v_fmac_f32_e32 v250, v56, v180
	v_fmac_f32_e32 v137, v48, v188
	v_fmac_f32_e32 v251, v40, v180
	v_fmac_f32_e32 v166, v32, v188
	v_mul_f32_e32 v167, 0xbfb8aa3b, v248
	v_mul_f32_e32 v213, 0xbfb8aa3b, v249
	v_mul_f32_e32 v214, 0xbfb8aa3b, v250
	v_mul_f32_e32 v215, 0xbfb8aa3b, v251
	v_exp_f32_e32 v167, v167
	v_exp_f32_e32 v213, v213
	v_exp_f32_e32 v214, v214
	v_exp_f32_e32 v215, v215
	v_add_f32_e32 v167, 1.0, v167
	v_add_f32_e32 v213, 1.0, v213
	v_add_f32_e32 v214, 1.0, v214
	v_add_f32_e32 v215, 1.0, v215
	v_rcp_f32_e32 v167, v167
	v_rcp_f32_e32 v213, v213
	v_rcp_f32_e32 v214, v214
	v_rcp_f32_e32 v215, v215
	v_mul_f32_e32 v248, v248, v254
	v_mul_f32_e32 v249, v249, v255
	v_mul_f32_e32 v250, v250, v137
	v_mul_f32_e32 v251, v251, v166
	v_mul_f32_e32 v56, v248, v167
	v_mul_f32_e32 v40, v249, v213
	v_mul_f32_e32 v24, v250, v214
	v_mul_f32_e32 v8, v251, v215
	v_mov_b32_dpp v244, v25 row_shr:1 row_mask:0xf bank_mask:0xf
	v_mov_b32_dpp v245, v9 row_shr:1 row_mask:0xf bank_mask:0xf
	v_mov_b32_dpp v246, v17 row_shr:1 row_mask:0xf bank_mask:0xf
	v_mov_b32_dpp v247, v1 row_shr:1 row_mask:0xf bank_mask:0xf
	v_fma_f32 v248, v57, v217, v233
	v_fma_f32 v254, v49, v225, v241
	v_fma_f32 v249, v41, v217, v233
	v_fma_f32 v255, v33, v225, v241
	v_fma_f32 v250, v25, v217, v233
	v_fma_f32 v137, v17, v225, v241
	v_fma_f32 v251, v9, v217, v233
	v_fma_f32 v166, v1, v225, v241
	v_fmac_f32_e32 v248, v245, v197
	v_fmac_f32_e32 v254, v247, v205
	v_fmac_f32_e32 v249, v57, v197
	v_fmac_f32_e32 v255, v49, v205
	v_fmac_f32_e32 v250, v41, v197
	v_fmac_f32_e32 v137, v33, v205
	v_fmac_f32_e32 v251, v25, v197
	v_fmac_f32_e32 v166, v17, v205
	v_fmac_f32_e32 v248, v244, v181
	v_fmac_f32_e32 v254, v246, v189
	v_fmac_f32_e32 v249, v245, v181
	v_fmac_f32_e32 v255, v247, v189
	v_fmac_f32_e32 v250, v57, v181
	v_fmac_f32_e32 v137, v49, v189
	v_fmac_f32_e32 v251, v41, v181
	v_fmac_f32_e32 v166, v33, v189
	v_mul_f32_e32 v167, 0xbfb8aa3b, v248
	v_mul_f32_e32 v213, 0xbfb8aa3b, v249
	v_mul_f32_e32 v214, 0xbfb8aa3b, v250
	v_mul_f32_e32 v215, 0xbfb8aa3b, v251
	v_exp_f32_e32 v167, v167
	v_exp_f32_e32 v213, v213
	v_exp_f32_e32 v214, v214
	v_exp_f32_e32 v215, v215
	v_add_f32_e32 v167, 1.0, v167
	v_add_f32_e32 v213, 1.0, v213
	v_add_f32_e32 v214, 1.0, v214
	v_add_f32_e32 v215, 1.0, v215
	v_rcp_f32_e32 v167, v167
	v_rcp_f32_e32 v213, v213
	v_rcp_f32_e32 v214, v214
	v_rcp_f32_e32 v215, v215
	v_mul_f32_e32 v248, v248, v254
	v_mul_f32_e32 v249, v249, v255
	v_mul_f32_e32 v250, v250, v137
	v_mul_f32_e32 v251, v251, v166
	v_mul_f32_e32 v57, v248, v167
	v_mul_f32_e32 v41, v249, v213
	v_mul_f32_e32 v25, v250, v214
	v_mul_f32_e32 v9, v251, v215
	v_mov_b32_dpp v244, v26 row_shr:1 row_mask:0xf bank_mask:0xf
	v_mov_b32_dpp v245, v10 row_shr:1 row_mask:0xf bank_mask:0xf
	v_mov_b32_dpp v246, v18 row_shr:1 row_mask:0xf bank_mask:0xf
	v_mov_b32_dpp v247, v2 row_shr:1 row_mask:0xf bank_mask:0xf
	v_fma_f32 v248, v58, v218, v234
	v_fma_f32 v254, v50, v226, v242
	v_fma_f32 v249, v42, v218, v234
	v_fma_f32 v255, v34, v226, v242
	v_fma_f32 v250, v26, v218, v234
	v_fma_f32 v137, v18, v226, v242
	v_fma_f32 v251, v10, v218, v234
	v_fma_f32 v166, v2, v226, v242
	v_fmac_f32_e32 v248, v245, v198
	v_fmac_f32_e32 v254, v247, v206
	v_fmac_f32_e32 v249, v58, v198
	v_fmac_f32_e32 v255, v50, v206
	v_fmac_f32_e32 v250, v42, v198
	v_fmac_f32_e32 v137, v34, v206
	v_fmac_f32_e32 v251, v26, v198
	v_fmac_f32_e32 v166, v18, v206
	v_fmac_f32_e32 v248, v244, v182
	v_fmac_f32_e32 v254, v246, v190
	v_fmac_f32_e32 v249, v245, v182
	v_fmac_f32_e32 v255, v247, v190
	v_fmac_f32_e32 v250, v58, v182
	v_fmac_f32_e32 v137, v50, v190
	v_fmac_f32_e32 v251, v42, v182
	v_fmac_f32_e32 v166, v34, v190
	v_mul_f32_e32 v167, 0xbfb8aa3b, v248
	v_mul_f32_e32 v213, 0xbfb8aa3b, v249
	v_mul_f32_e32 v214, 0xbfb8aa3b, v250
	v_mul_f32_e32 v215, 0xbfb8aa3b, v251
	v_exp_f32_e32 v167, v167
	v_exp_f32_e32 v213, v213
	v_exp_f32_e32 v214, v214
	v_exp_f32_e32 v215, v215
	v_add_f32_e32 v167, 1.0, v167
	v_add_f32_e32 v213, 1.0, v213
	v_add_f32_e32 v214, 1.0, v214
; __device__ __forceinline__ float siluf_(float x) { return x * __builtin_amdgcn_rcpf(1.f + __expf(-x)); }
; template <int NT, bool SAMPLE>
; __device__ __forceinline__ void ffn_item(const bf16_t* U, int row0, bool has_hist, const float* st, int cgi, const float* w, const float* bias, bf16_t* ACT, float* state_out) {
;     ...
; #pragma unroll
;     for (int t = 0; t < NT; ++t) {
;         float cg_[8], cv_[8], o[8];
;         unpack8(rg[t], cg_); unpack8(rv[t], cv_);
; #pragma unroll
;         for (int e = 0; e < 8; ++e) {
;             const float gg = g0[e] * wg[0][e] + g1[e] * wg[1][e] + cg_[e] * wg[2][e] + bg[e];
;             const float vv = v0[e] * wv[0][e] + v1[e] * wv[1][e] + cv_[e] * wv[2][e] + bvv[e];
;             o[e] = siluf_(gg) * vv; g0[e] = g1[e]; g1[e] = cg_[e]; v0[e] = v1[e]; v1[e] = cv_[e]; }
;         *(u32x4*)(ACT + (size_t)(row0 + t) * FF + c0) = pack8(o);
	v_add_f32_e32 v215, 1.0, v215
	v_rcp_f32_e32 v167, v167
	v_rcp_f32_e32 v213, v213
	v_rcp_f32_e32 v214, v214
	v_rcp_f32_e32 v215, v215
	v_mul_f32_e32 v248, v248, v254
	v_mul_f32_e32 v249, v249, v255
	v_mul_f32_e32 v250, v250, v137
	v_mul_f32_e32 v251, v251, v166
	v_mul_f32_e32 v58, v248, v167
	v_mul_f32_e32 v42, v249, v213
	v_mul_f32_e32 v26, v250, v214
	v_mul_f32_e32 v10, v251, v215
	v_mov_b32_dpp v244, v27 row_shr:1 row_mask:0xf bank_mask:0xf
	v_mov_b32_dpp v245, v11 row_shr:1 row_mask:0xf bank_mask:0xf
	v_mov_b32_dpp v246, v19 row_shr:1 row_mask:0xf bank_mask:0xf
	v_mov_b32_dpp v247, v3 row_shr:1 row_mask:0xf bank_mask:0xf
	v_fma_f32 v248, v59, v219, v235
	v_fma_f32 v254, v51, v227, v243
	v_fma_f32 v249, v43, v219, v235
	v_fma_f32 v255, v35, v227, v243
	v_fma_f32 v250, v27, v219, v235
	v_fma_f32 v137, v19, v227, v243
	v_fma_f32 v251, v11, v219, v235
	v_fma_f32 v166, v3, v227, v243
	v_fmac_f32_e32 v248, v245, v199
	v_fmac_f32_e32 v254, v247, v207
	v_fmac_f32_e32 v249, v59, v199
	v_fmac_f32_e32 v255, v51, v207
	v_fmac_f32_e32 v250, v43, v199
	v_fmac_f32_e32 v137, v35, v207
	v_fmac_f32_e32 v251, v27, v199
	v_fmac_f32_e32 v166, v19, v207
	v_fmac_f32_e32 v248, v244, v183
	v_fmac_f32_e32 v254, v246, v191
	v_fmac_f32_e32 v249, v245, v183
	v_fmac_f32_e32 v255, v247, v191
	v_fmac_f32_e32 v250, v59, v183
	v_fmac_f32_e32 v137, v51, v191
	v_fmac_f32_e32 v251, v43, v183
	v_fmac_f32_e32 v166, v35, v191
	v_mul_f32_e32 v167, 0xbfb8aa3b, v248
	v_mul_f32_e32 v213, 0xbfb8aa3b, v249
	v_mul_f32_e32 v214, 0xbfb8aa3b, v250
	v_mul_f32_e32 v215, 0xbfb8aa3b, v251
	v_exp_f32_e32 v167, v167
	v_exp_f32_e32 v213, v213
	v_exp_f32_e32 v214, v214
	v_exp_f32_e32 v215, v215
	v_add_f32_e32 v167, 1.0, v167
	v_add_f32_e32 v213, 1.0, v213
	v_add_f32_e32 v214, 1.0, v214
	v_add_f32_e32 v215, 1.0, v215
	v_rcp_f32_e32 v167, v167
	v_rcp_f32_e32 v213, v213
	v_rcp_f32_e32 v214, v214
	v_rcp_f32_e32 v215, v215
	v_mul_f32_e32 v248, v248, v254
	v_mul_f32_e32 v249, v249, v255
	v_mul_f32_e32 v250, v250, v137
	v_mul_f32_e32 v251, v251, v166
	v_mul_f32_e32 v59, v248, v167
	v_mul_f32_e32 v43, v249, v213
	v_mul_f32_e32 v27, v250, v214
	v_mul_f32_e32 v11, v251, v215
	s_mov_b32 exec_lo, 0xfffcfffc
	s_mov_b32 exec_hi, 0xfffcfffc
	v_cvt_pk_bf16_f32 v168, v124, v125
	v_cvt_pk_bf16_f32 v169, v126, v127
	v_cvt_pk_bf16_f32 v170, v120, v121
	v_cvt_pk_bf16_f32 v171, v122, v123
	global_store_dwordx4 v136, v[168:171], s[14:15]
	s_add_u32 s14, s14, 0x2b00
	s_addc_u32 s15, s15, 0
	v_cvt_pk_bf16_f32 v172, v108, v109
	v_cvt_pk_bf16_f32 v173, v110, v111
	v_cvt_pk_bf16_f32 v174, v104, v105
	v_cvt_pk_bf16_f32 v175, v106, v107
	global_store_dwordx4 v136, v[172:175], s[14:15]
	s_add_u32 s14, s14, 0x2b00
	s_addc_u32 s15, s15, 0
	v_cvt_pk_bf16_f32 v168, v92, v93
	v_cvt_pk_bf16_f32 v169, v94, v95
	v_cvt_pk_bf16_f32 v170, v88, v89
	v_cvt_pk_bf16_f32 v171, v90, v91
	global_store_dwordx4 v136, v[168:171], s[14:15]
	s_add_u32 s14, s14, 0x2b00
	s_addc_u32 s15, s15, 0
	v_cvt_pk_bf16_f32 v172, v76, v77
	v_cvt_pk_bf16_f32 v173, v78, v79
	v_cvt_pk_bf16_f32 v174, v72, v73
	v_cvt_pk_bf16_f32 v175, v74, v75
	global_store_dwordx4 v136, v[172:175], s[14:15]
	s_add_u32 s14, s14, 0x14ff00
	s_addc_u32 s15, s15, 0
	v_cvt_pk_bf16_f32 v168, v60, v61
	v_cvt_pk_bf16_f32 v169, v62, v63
	v_cvt_pk_bf16_f32 v170, v56, v57
	v_cvt_pk_bf16_f32 v171, v58, v59
	global_store_dwordx4 v136, v[168:171], s[14:15]
	s_add_u32 s14, s14, 0x2b00
	s_addc_u32 s15, s15, 0
	v_cvt_pk_bf16_f32 v172, v44, v45
	v_cvt_pk_bf16_f32 v173, v46, v47
	v_cvt_pk_bf16_f32 v174, v40, v41
	v_cvt_pk_bf16_f32 v175, v42, v43
	global_store_dwordx4 v136, v[172:175], s[14:15]
	s_add_u32 s14, s14, 0x2b00
	s_addc_u32 s15, s15, 0
	v_cvt_pk_bf16_f32 v168, v28, v29
	v_cvt_pk_bf16_f32 v169, v30, v31
	v_cvt_pk_bf16_f32 v170, v24, v25
	v_cvt_pk_bf16_f32 v171, v26, v27
	global_store_dwordx4 v136, v[168:171], s[14:15]
	s_add_u32 s14, s14, 0x2b00
	s_addc_u32 s15, s15, 0
	v_cvt_pk_bf16_f32 v172, v12, v13
	v_cvt_pk_bf16_f32 v173, v14, v15
	v_cvt_pk_bf16_f32 v174, v8, v9
	v_cvt_pk_bf16_f32 v175, v10, v11
	global_store_dwordx4 v136, v[172:175], s[14:15]
	s_mov_b64 exec, -1
	s_branch .Lepi7_done
; __device__ __forceinline__ unsigned cvt_pk_bf16(float lo, float hi) { unsigned r; asm volatile("v_cvt_pk_bf16_f32 %0, %1, %2" : "=v"(r) : "v"(lo), "v"(hi)); return r; }
;     __device__ __forceinline__ void operator()(const f32x4 (&acc)[2][2][4][2], const Unit& u, int wr, int wc, int fr, int fq) const {
;     ...
;         const int col0 = u.pn * BM + wc * 32 + 8 * fq;
;         float rs[2][4];
; #pragma unroll
;         for (int ai = 0; ai < 2; ++ai)
; #pragma unroll
;             for (int m = 0; m < 4; ++m) rs[ai][m] = ssq ? rsqrtf(ssq[row0 + ai * HALF + m * 16] * (1.f / DM) + EPS) : 1.f;
; #pragma unroll
;         for (int ai = 0; ai < 2; ++ai)
; #pragma unroll
;             for (int m = 0; m < 4; ++m) { bf16_t* rowp = O + (size_t)(row0 + ai * HALF + m * 16) * ldc + col0;
; #pragma unroll
;                 for (int bj = 0; bj < 2; ++bj) { const f32x4 v0 = acc[ai][bj][m][0] * rs[ai][m], v1 = acc[ai][bj][m][1] * rs[ai][m];
;                     u32x4 w; w.x = cvt_pk_bf16(v0[0], v0[1]); w.y = cvt_pk_bf16(v0[2], v0[3]); w.z = cvt_pk_bf16(v1[0], v1[1]); w.w = cvt_pk_bf16(v1[2], v1[3]);
;                     *(u32x4*)(rowp + bj * HALF) = w; } }
.Lepi7_sample:
	v_cvt_pk_bf16_f32 v168, v124, v125
	v_cvt_pk_bf16_f32 v169, v126, v127
	v_cvt_pk_bf16_f32 v170, v120, v121
	v_cvt_pk_bf16_f32 v171, v122, v123
	v_cvt_pk_bf16_f32 v172, v116, v117
	v_cvt_pk_bf16_f32 v173, v118, v119
	v_cvt_pk_bf16_f32 v174, v112, v113
	v_cvt_pk_bf16_f32 v175, v114, v115
	global_store_dwordx4 v152, v[168:171], s[10:11]
	global_store_dwordx4 v152, v[172:175], s[12:13]
	s_add_u32 s10, s10, 0x5600
	s_addc_u32 s11, s11, 0
	s_add_u32 s12, s12, 0x5600
	s_addc_u32 s13, s13, 0
	v_cvt_pk_bf16_f32 v168, v108, v109
	v_cvt_pk_bf16_f32 v169, v110, v111
	v_cvt_pk_bf16_f32 v170, v104, v105
	v_cvt_pk_bf16_f32 v171, v106, v107
	v_cvt_pk_bf16_f32 v172, v100, v101
	v_cvt_pk_bf16_f32 v173, v102, v103
	v_cvt_pk_bf16_f32 v174, v96, v97
	v_cvt_pk_bf16_f32 v175, v98, v99
	global_store_dwordx4 v152, v[168:171], s[10:11]
	global_store_dwordx4 v152, v[172:175], s[12:13]
	s_add_u32 s10, s10, 0x5600
	s_addc_u32 s11, s11, 0
	s_add_u32 s12, s12, 0x5600
	s_addc_u32 s13, s13, 0
	v_cvt_pk_bf16_f32 v168, v92, v93
	v_cvt_pk_bf16_f32 v169, v94, v95
	v_cvt_pk_bf16_f32 v170, v88, v89
	v_cvt_pk_bf16_f32 v171, v90, v91
	v_cvt_pk_bf16_f32 v172, v84, v85
	v_cvt_pk_bf16_f32 v173, v86, v87
	v_cvt_pk_bf16_f32 v174, v80, v81
	v_cvt_pk_bf16_f32 v175, v82, v83
	global_store_dwordx4 v152, v[168:171], s[10:11]
	global_store_dwordx4 v152, v[172:175], s[12:13]
	s_add_u32 s10, s10, 0x5600
	s_addc_u32 s11, s11, 0
	s_add_u32 s12, s12, 0x5600
	s_addc_u32 s13, s13, 0
	v_cvt_pk_bf16_f32 v168, v76, v77
	v_cvt_pk_bf16_f32 v169, v78, v79
	v_cvt_pk_bf16_f32 v170, v72, v73
	v_cvt_pk_bf16_f32 v171, v74, v75
	v_cvt_pk_bf16_f32 v172, v68, v69
	v_cvt_pk_bf16_f32 v173, v70, v71
	v_cvt_pk_bf16_f32 v174, v64, v65
	v_cvt_pk_bf16_f32 v175, v66, v67
	global_store_dwordx4 v152, v[168:171], s[10:11]
	global_store_dwordx4 v152, v[172:175], s[12:13]
	s_add_u32 s10, s10, 0x29fe00
	s_addc_u32 s11, s11, 0
	s_add_u32 s12, s12, 0x29fe00
	s_addc_u32 s13, s13, 0
	v_cvt_pk_bf16_f32 v168, v60, v61
	v_cvt_pk_bf16_f32 v169, v62, v63
	v_cvt_pk_bf16_f32 v170, v56, v57
	v_cvt_pk_bf16_f32 v171, v58, v59
	v_cvt_pk_bf16_f32 v172, v52, v53
	v_cvt_pk_bf16_f32 v173, v54, v55
	v_cvt_pk_bf16_f32 v174, v48, v49
	v_cvt_pk_bf16_f32 v175, v50, v51
	global_store_dwordx4 v152, v[168:171], s[10:11]
	global_store_dwordx4 v152, v[172:175], s[12:13]
	s_add_u32 s10, s10, 0x5600
	s_addc_u32 s11, s11, 0
	s_add_u32 s12, s12, 0x5600
	s_addc_u32 s13, s13, 0
	v_cvt_pk_bf16_f32 v168, v44, v45
	v_cvt_pk_bf16_f32 v169, v46, v47
	v_cvt_pk_bf16_f32 v170, v40, v41
	v_cvt_pk_bf16_f32 v171, v42, v43
	v_cvt_pk_bf16_f32 v172, v36, v37
	v_cvt_pk_bf16_f32 v173, v38, v39
	v_cvt_pk_bf16_f32 v174, v32, v33
	v_cvt_pk_bf16_f32 v175, v34, v35
	global_store_dwordx4 v152, v[168:171], s[10:11]
	global_store_dwordx4 v152, v[172:175], s[12:13]
	s_add_u32 s10, s10, 0x5600
	s_addc_u32 s11, s11, 0
	s_add_u32 s12, s12, 0x5600
	s_addc_u32 s13, s13, 0
	v_cvt_pk_bf16_f32 v168, v28, v29
	v_cvt_pk_bf16_f32 v169, v30, v31
	v_cvt_pk_bf16_f32 v170, v24, v25
	v_cvt_pk_bf16_f32 v171, v26, v27
	v_cvt_pk_bf16_f32 v172, v20, v21
	v_cvt_pk_bf16_f32 v173, v22, v23
	v_cvt_pk_bf16_f32 v174, v16, v17
	v_cvt_pk_bf16_f32 v175, v18, v19
	global_store_dwordx4 v152, v[168:171], s[10:11]
	global_store_dwordx4 v152, v[172:175], s[12:13]
	s_add_u32 s10, s10, 0x5600
	s_addc_u32 s11, s11, 0
	s_add_u32 s12, s12, 0x5600
	s_addc_u32 s13, s13, 0
	v_cvt_pk_bf16_f32 v168, v12, v13
	v_cvt_pk_bf16_f32 v169, v14, v15
	v_cvt_pk_bf16_f32 v170, v8, v9
	v_cvt_pk_bf16_f32 v171, v10, v11
	v_cvt_pk_bf16_f32 v172, v4, v5
	v_cvt_pk_bf16_f32 v173, v6, v7
	v_cvt_pk_bf16_f32 v174, v0, v1
	v_cvt_pk_bf16_f32 v175, v2, v3
	global_store_dwordx4 v152, v[168:171], s[10:11]
	global_store_dwordx4 v152, v[172:175], s[12:13]
.Lepi7_done:
	s_and_b64 vcc, exec, s[4:5]
	s_cbranch_vccnz .LBB0_820
	s_andn2_b64 vcc, exec, s[20:21]
	s_cbranch_vccnz .LBB0_800
	s_barrier
	s_branch .LBB0_800

; __device__ __forceinline__ int ltid() { int t = threadIdx.x; asm volatile("" : "+v"(t)); return t; }
; __device__ __forceinline__ KArgs ka_get() { KArgs p = (KArgs)__builtin_amdgcn_kernarg_segment_ptr(); asm volatile("" : "+s"(p)); return p; }
; __global__ void __launch_bounds__(512, 2) mk_fwd(Args args) {
;     ...
;     if (IN(8)) { const KArgs KA = ka_get(); const int tid = ltid(), lane = tid & 63, wave = __builtin_amdgcn_readfirstlane(tid >> 6); (void)lane; (void)wave;
;         const int gt = vbx * 512 + tid, NGT = G * 512;
;         for (int it = gt; it < (MP / 8) * 688; it += NGT) { const int cgi = it % 688, tg = it / 688; const int row0 = tg * 8, t0 = row0 % SEQ, b = row0 / SEQ;
;             ffn_item<8, false>(U, row0, t0 > 0, nullptr, cgi, ffn_conv_w, ffn_conv_b, ACT, (t0 == SEQ - 8) ? out + O_PFFC + (size_t)b * 2 * FF2 : nullptr); }
.LBB0_876:
	s_cmp_lt_i32 s88, 9
	s_cselect_b64 s[0:1], -1, 0
	s_and_b64 s[0:1], s[0:1], s[4:5]
	s_andn2_b64 vcc, exec, s[0:1]
	s_cbranch_vccnz .LBB0_890
	s_mov_b64 s[8:9], s[96:97]
	s_waitcnt vmcnt(0)
	v_mov_b32_e32 v0, v212
	v_readlane_b32 s3, v253, 2
	s_mov_b32 s4, 0x15800
	s_nop 0
	v_lshl_add_u32 v182, s3, 9, v0
	s_lshl_b32 s3, s94, 9
	v_cmp_gt_i32_e32 vcc, s4, v182
	v_lshlrev_b32_e32 v183, 3, v182
	s_and_saveexec_b64 s[10:11], vcc
	s_cbranch_execz .LBB0_886
	s_load_dwordx2 s[16:17], s[8:9], 0xd0
	s_load_dwordx4 s[4:7], s[8:9], 0xa8
	s_mov_b64 s[12:13], 0x5600
	s_mov_b64 s[20:21], 0xac00
	s_mov_b64 s[24:25], 0x10200
	s_waitcnt lgkmcnt(0)
	s_add_u32 s14, s16, 0x9890000
	s_addc_u32 s15, s17, 0
	s_add_u32 s16, s16, 0x168d0000
	s_addc_u32 s17, s17, 0
	s_add_u32 s18, s4, 0x5600
	s_addc_u32 s19, s5, 0
	s_add_u32 s22, s4, 0xac00
	s_addc_u32 s23, s5, 0
	s_add_u32 s26, s4, 0x10200
	s_addc_u32 s27, s5, 0
	s_add_u32 s28, s4, 0x15800
	s_addc_u32 s29, s5, 0
	s_add_u32 s30, s4, 0x1ae00
	s_addc_u32 s31, s5, 0
	s_add_u32 s34, s6, 0x5600
	s_addc_u32 s35, s7, 0
	v_lshlrev_b32_e32 v184, 3, v182
	s_lshl_b32 s33, s3, 3
	s_mov_b64 s[36:37], 0
	s_mov_b32 s42, 0x2fa0be83
	s_movk_i32 s43, 0x7f8
	s_movk_i32 s44, 0x5600
	s_mov_b64 s[38:39], 0x4914000
	s_movk_i32 s45, 0x2000
	s_movk_i32 s46, 0x2b00
	s_mov_b32 s47, 0x157ff
	v_mov_b32_e32 v185, v182
	s_branch .LBB0_880

; __global__ void __launch_bounds__(512, 2) mk_fwd(Args args) {
;     ...
;         for (int it = gt; it < (MP / 8) * 688; it += NGT) { const int cgi = it % 688, tg = it / 688; const int row0 = tg * 8, t0 = row0 % SEQ, b = row0 / SEQ;
;             ffn_item<8, false>(U, row0, t0 > 0, nullptr, cgi, ffn_conv_w, ffn_conv_b, ACT, (t0 == SEQ - 8) ? out + O_PFFC + (size_t)b * 2 * FF2 : nullptr); }
.LBB0_880:
	v_mul_hi_i32 v1, v185, s42
	v_lshrrev_b32_e32 v2, 31, v1
	v_ashrrev_i32_e32 v0, 7, v1
	v_add_u32_e32 v0, v0, v2
	v_ashrrev_i32_e32 v3, 31, v0
	v_lshlrev_b32_e32 v192, 6, v0
	v_lshrrev_b32_e32 v3, 21, v3
	v_add_u32_e32 v3, v192, v3
	v_and_b32_e32 v3, 0xfffff800, v3
	v_sub_u32_e32 v32, v192, v3
	v_cmp_eq_u32_e32 vcc, s43, v32
	v_mov_b64_e32 v[128:129], 0
	s_and_saveexec_b64 s[40:41], vcc
	s_cbranch_execz .LBB0_882
	s_load_dwordx2 s[48:49], s[8:9], 0xc8
	v_ashrrev_i32_e32 v1, 15, v1
	v_add_u32_e32 v1, v1, v2
	v_mul_i32_i24_e32 v2, 0x5600, v1
	v_ashrrev_i32_e32 v3, 31, v2
	s_waitcnt lgkmcnt(0)
	v_lshl_add_u64 v[2:3], v[2:3], 2, s[48:49]
	v_lshl_add_u64 v[128:129], v[2:3], 0, s[38:39]
